# GEMM loops: dropped s_setprio flips and the redundant lgkmcnt(0) after the barrier in all 24 compute blocks
# speedup vs baseline: 1.0103x; 1.0103x over previous
; #define PG8_STAGE(bufoff, gbase, voff) do { _Pragma("unroll") for (int _i = 0; _i < 2; ++_i) \
;         __builtin_amdgcn_global_load_lds((const unsigned*)((const char*)(gbase) + (voff)[_i]), (PG8_LAS unsigned*)(lds + (bufoff) + ldsw + _i * 8192), 16, 0, 0); } while (0)
; #define PG8_LDA(dst, b, h) do { _Pragma("unroll") for (int m = 0; m < 4; ++m) _Pragma("unroll") for (int k = 0; k < 2; ++k) dst[m][k] = *(const PG8_LAS bf16x8*)(lds + PG8_SA(b, h) + aoffk[k] + m * 2048); } while (0)
; #define PG8_LDB(dst, b, h) do { _Pragma("unroll") for (int n = 0; n < 2; ++n) _Pragma("unroll") for (int k = 0; k < 2; ++k) dst[n][k] = *(const PG8_LAS bf16x8*)(lds + PG8_SB(b, h) + boffk[k] + n * 2048); } while (0)
; #define PG8_MMA(ai, bj, At, Bt) do { __builtin_amdgcn_s_setprio(1); _Pragma("unroll") for (int m = 0; m < 4; ++m) _Pragma("unroll") for (int n = 0; n < 2; ++n) _Pragma("unroll") for (int k = 0; k < 2; ++k) \
;         acc[ai][bj][m][n] = __builtin_amdgcn_mfma_f32_16x16x32_bf16(Bt[n][k], At[m][k], acc[ai][bj][m][n], 0, 0, 0); __builtin_amdgcn_s_setprio(0); } while (0)
; #define PG8_WAIT_V(n) asm volatile("s_waitcnt vmcnt(" #n ")" ::: "memory")
; #define PG8_WAIT_L(n) asm volatile("s_waitcnt lgkmcnt(" #n ")" ::: "memory")
; #define PG8_BAR __builtin_amdgcn_s_barrier()
; template <class Epi, class Sched, bool ALIGN_EPI = false, bool SP2 = false>
; __device__ __forceinline__ void gemm_phase(PG8_LAS unsigned char* lds, const Gemm g, const Sched& S, const Epi& E) {
;     ...
;             const bool last = (t == nt - 2);
;             const char* a1 = cA + (size_t)(t + 1) * kstep;
;             const char* a2 = last ? nA : cA + (size_t)(t + 2) * kstep; const char* b2 = last ? nB : cB + (size_t)(t + 2) * kstep;
;             const char* a3 = a2 + kstep; const char* b3 = b2 + kstep;
;             if (last && has_next) S.a_ready(nxt);
;             if constexpr (SP2) {
;             PG8_LDB(B0, 0, 0); PG8_LDB(B1, 0, 1); PG8_SCHED; PG8_LDA(At, 0, 0); PG8_STAGE(PG8_SA(1, 1), a1 + hstepA, voffA);
;             PG8_WAIT_V(8); PG8_WAIT_L(0); PG8_BAR; PG8_MMA(0, 0, At, B0); PG8_MMA(0, 1, At, B1); PG8_BAR; PG8_SCHED;
;             PG8_LDA(At, 0, 1); PG8_STAGE(PG8_SB(0, 0), b2, voffB); PG8_STAGE(PG8_SB(0, 1), b2 + hstepB, voffB); PG8_STAGE(PG8_SA(0, 0), a2, voffA);
;             PG8_WAIT_V(8); PG8_WAIT_L(0); PG8_BAR; PG8_MMA(1, 0, At, B0); PG8_MMA(1, 1, At, B1); PG8_BAR; PG8_SCHED;
.LBB0_296:
	s_add_u32 s22, s20, 0xfff80080
	s_addc_u32 s23, s21, -1
	s_add_i32 s47, 0, 0x10000
	s_cmp_eq_u32 s46, 28
	s_cselect_b32 s25, s11, s23
	s_cselect_b32 s24, s33, s22
	s_cselect_b32 s23, s9, s45
	s_cselect_b32 s22, s43, s44
	s_add_i32 s50, 0, 0x14000
	v_add_u32_e32 v142, s47, v147
	v_add_u32_e32 v156, s47, v148
	v_add_u32_e32 v168, s50, v147
	v_add_u32_e32 v176, s50, v148
	ds_read_b128 v[142:145], v142
	ds_read_b128 v[156:159], v156
	ds_read_b128 v[160:163], v150
	ds_read_b128 v[164:167], v151
	ds_read_b128 v[172:175], v168
	ds_read_b128 v[176:179], v176
	ds_read_b128 v[180:183], v152
	ds_read_b128 v[184:187], v153
	v_lshl_add_u64 v[212:213], s[20:21], 0, v[138:139]
	s_add_i32 m0, s36, 0xc000
	ds_read_b128 v[188:191], v154
	ds_read_b128 v[192:195], v154 offset:1024
	ds_read_b128 v[196:199], v154 offset:2048
	ds_read_b128 v[200:203], v154 offset:3072
	ds_read_b128 v[204:207], v154 offset:4096
	ds_read_b128 v[208:211], v154 offset:5120
	ds_read_b128 v[226:229], v154 offset:6144
	ds_read_b128 v[230:233], v154 offset:7168
	global_load_lds_dwordx4 v[212:213], off
	v_lshl_add_u64 v[212:213], s[20:21], 0, v[140:141]
	s_add_i32 m0, s36, 0xe000
	s_nop 0
	global_load_lds_dwordx4 v[212:213], off
	s_waitcnt vmcnt(8)
	s_waitcnt lgkmcnt(0)
	s_barrier
	v_mfma_f32_16x16x32_bf16 v[128:131], v[142:145], v[188:191], v[128:131]
	v_mfma_f32_16x16x32_bf16 v[120:123], v[160:163], v[188:191], v[120:123]
	v_mfma_f32_16x16x32_bf16 v[112:115], v[142:145], v[196:199], v[112:115]
	v_mfma_f32_16x16x32_bf16 v[104:107], v[160:163], v[196:199], v[104:107]
	v_mfma_f32_16x16x32_bf16 v[96:99], v[142:145], v[204:207], v[96:99]
	v_mfma_f32_16x16x32_bf16 v[88:91], v[160:163], v[204:207], v[88:91]
	v_mfma_f32_16x16x32_bf16 v[80:83], v[142:145], v[226:229], v[80:83]
	v_mfma_f32_16x16x32_bf16 v[72:75], v[160:163], v[226:229], v[72:75]
	v_mfma_f32_16x16x32_bf16 v[128:131], v[156:159], v[192:195], v[128:131]
	v_mfma_f32_16x16x32_bf16 v[120:123], v[164:167], v[192:195], v[120:123]
	v_mfma_f32_16x16x32_bf16 v[112:115], v[156:159], v[200:203], v[112:115]
	v_mfma_f32_16x16x32_bf16 v[104:107], v[164:167], v[200:203], v[104:107]
	v_mfma_f32_16x16x32_bf16 v[96:99], v[156:159], v[208:211], v[96:99]
	v_mfma_f32_16x16x32_bf16 v[88:91], v[164:167], v[208:211], v[88:91]
	v_mfma_f32_16x16x32_bf16 v[80:83], v[156:159], v[230:233], v[80:83]
	v_mfma_f32_16x16x32_bf16 v[72:75], v[164:167], v[230:233], v[72:75]
	v_mfma_f32_16x16x32_bf16 v[124:127], v[172:175], v[188:191], v[124:127]
	v_mfma_f32_16x16x32_bf16 v[116:119], v[180:183], v[188:191], v[116:119]
	v_mfma_f32_16x16x32_bf16 v[108:111], v[172:175], v[196:199], v[108:111]
	v_mfma_f32_16x16x32_bf16 v[100:103], v[180:183], v[196:199], v[100:103]
	v_mfma_f32_16x16x32_bf16 v[92:95], v[172:175], v[204:207], v[92:95]
	v_mfma_f32_16x16x32_bf16 v[84:87], v[180:183], v[204:207], v[84:87]
	v_mfma_f32_16x16x32_bf16 v[76:79], v[172:175], v[226:229], v[76:79]
	v_mfma_f32_16x16x32_bf16 v[68:71], v[180:183], v[226:229], v[68:71]
	v_mfma_f32_16x16x32_bf16 v[124:127], v[176:179], v[192:195], v[124:127]
	v_mfma_f32_16x16x32_bf16 v[116:119], v[184:187], v[192:195], v[116:119]
	v_mfma_f32_16x16x32_bf16 v[108:111], v[176:179], v[200:203], v[108:111]
	v_mfma_f32_16x16x32_bf16 v[100:103], v[184:187], v[200:203], v[100:103]
	v_mfma_f32_16x16x32_bf16 v[92:95], v[176:179], v[208:211], v[92:95]
	v_mfma_f32_16x16x32_bf16 v[84:87], v[184:187], v[208:211], v[84:87]
	v_mfma_f32_16x16x32_bf16 v[76:79], v[176:179], v[230:233], v[76:79]
	v_mfma_f32_16x16x32_bf16 v[68:71], v[184:187], v[230:233], v[68:71]
	s_barrier
	s_add_i32 s47, s47, s34
	v_lshl_add_u64 v[212:213], s[22:23], 0, v[2:3]
	s_mov_b32 m0, s47
	ds_read_b128 v[188:191], v154 offset:16384
	ds_read_b128 v[192:195], v154 offset:17408
	ds_read_b128 v[196:199], v154 offset:18432
	ds_read_b128 v[200:203], v154 offset:19456
	ds_read_b128 v[204:207], v154 offset:20480
	ds_read_b128 v[208:211], v154 offset:21504
	ds_read_b128 v[226:229], v154 offset:22528
	ds_read_b128 v[230:233], v154 offset:23552
	global_load_lds_dwordx4 v[212:213], off
	s_add_i32 m0, s47, 0x2000
	s_add_u32 s48, s22, 0x80000
	v_lshl_add_u64 v[234:235], s[22:23], 0, v[132:133]
	s_addc_u32 s49, s23, 0
	s_add_i32 s47, s50, s34
	global_load_lds_dwordx4 v[234:235], off
	v_lshl_add_u64 v[236:237], s[48:49], 0, v[2:3]
	s_mov_b32 m0, s47
	v_lshl_add_u64 v[238:239], s[24:25], 0, v[134:135]
	global_load_lds_dwordx4 v[236:237], off
	v_lshl_add_u64 v[236:237], s[48:49], 0, v[132:133]
	s_add_i32 m0, s47, 0x2000
	s_nop 0
	global_load_lds_dwordx4 v[236:237], off
	v_lshl_add_u64 v[236:237], s[24:25], 0, v[136:137]
	s_mov_b32 m0, s36
	s_nop 0
	global_load_lds_dwordx4 v[236:237], off
	s_mov_b32 m0, s37
	s_nop 0
	global_load_lds_dwordx4 v[238:239], off
	s_waitcnt vmcnt(8)
	s_waitcnt lgkmcnt(0)
	s_barrier
; #define PG8_STAGE(bufoff, gbase, voff) do { _Pragma("unroll") for (int _i = 0; _i < 2; ++_i) \
;         __builtin_amdgcn_global_load_lds((const unsigned*)((const char*)(gbase) + (voff)[_i]), (PG8_LAS unsigned*)(lds + (bufoff) + ldsw + _i * 8192), 16, 0, 0); } while (0)
; #define PG8_LDA(dst, b, h) do { _Pragma("unroll") for (int m = 0; m < 4; ++m) _Pragma("unroll") for (int k = 0; k < 2; ++k) dst[m][k] = *(const PG8_LAS bf16x8*)(lds + PG8_SA(b, h) + aoffk[k] + m * 2048); } while (0)
; #define PG8_LDB(dst, b, h) do { _Pragma("unroll") for (int n = 0; n < 2; ++n) _Pragma("unroll") for (int k = 0; k < 2; ++k) dst[n][k] = *(const PG8_LAS bf16x8*)(lds + PG8_SB(b, h) + boffk[k] + n * 2048); } while (0)
; #define PG8_MMA(ai, bj, At, Bt) do { __builtin_amdgcn_s_setprio(1); _Pragma("unroll") for (int m = 0; m < 4; ++m) _Pragma("unroll") for (int n = 0; n < 2; ++n) _Pragma("unroll") for (int k = 0; k < 2; ++k) \
;         acc[ai][bj][m][n] = __builtin_amdgcn_mfma_f32_16x16x32_bf16(Bt[n][k], At[m][k], acc[ai][bj][m][n], 0, 0, 0); __builtin_amdgcn_s_setprio(0); } while (0)
; #define PG8_WAIT_V(n) asm volatile("s_waitcnt vmcnt(" #n ")" ::: "memory")
; #define PG8_WAIT_L(n) asm volatile("s_waitcnt lgkmcnt(" #n ")" ::: "memory")
; #define PG8_BAR __builtin_amdgcn_s_barrier()
; #define PG8_SCHED __builtin_amdgcn_sched_barrier(0)
; template <class Epi, class Sched, bool ALIGN_EPI = false, bool SP2 = false>
; __device__ __forceinline__ void gemm_phase(PG8_LAS unsigned char* lds, const Gemm g, const Sched& S, const Epi& E) {
;     ...
;             PG8_WAIT_V(8); PG8_WAIT_L(0); PG8_BAR; PG8_MMA(1, 0, At, B0); PG8_MMA(1, 1, At, B1); PG8_BAR; PG8_SCHED;
;             PG8_LDB(B0, 1, 0); PG8_LDB(B1, 1, 1); PG8_SCHED; PG8_LDA(At, 1, 0); PG8_STAGE(PG8_SA(0, 1), a2 + hstepA, voffA);
;             PG8_WAIT_V(8); PG8_WAIT_L(0); PG8_BAR; PG8_MMA(0, 0, At, B0); PG8_MMA(0, 1, At, B1); PG8_BAR; PG8_SCHED;
	v_mfma_f32_16x16x32_bf16 v[64:67], v[142:145], v[188:191], v[64:67]
	v_mfma_f32_16x16x32_bf16 v[56:59], v[160:163], v[188:191], v[56:59]
	v_mfma_f32_16x16x32_bf16 v[48:51], v[142:145], v[196:199], v[48:51]
	v_mfma_f32_16x16x32_bf16 v[40:43], v[160:163], v[196:199], v[40:43]
	v_mfma_f32_16x16x32_bf16 v[32:35], v[142:145], v[204:207], v[32:35]
	v_mfma_f32_16x16x32_bf16 v[24:27], v[160:163], v[204:207], v[24:27]
	v_mfma_f32_16x16x32_bf16 v[16:19], v[142:145], v[226:229], v[16:19]
	v_mfma_f32_16x16x32_bf16 v[8:11], v[160:163], v[226:229], v[8:11]
	v_mfma_f32_16x16x32_bf16 v[64:67], v[156:159], v[192:195], v[64:67]
	v_mfma_f32_16x16x32_bf16 v[56:59], v[164:167], v[192:195], v[56:59]
	v_mfma_f32_16x16x32_bf16 v[48:51], v[156:159], v[200:203], v[48:51]
	v_mfma_f32_16x16x32_bf16 v[40:43], v[164:167], v[200:203], v[40:43]
	v_mfma_f32_16x16x32_bf16 v[32:35], v[156:159], v[208:211], v[32:35]
	v_mfma_f32_16x16x32_bf16 v[24:27], v[164:167], v[208:211], v[24:27]
	v_mfma_f32_16x16x32_bf16 v[16:19], v[156:159], v[230:233], v[16:19]
	v_mfma_f32_16x16x32_bf16 v[8:11], v[164:167], v[230:233], v[8:11]
	v_mfma_f32_16x16x32_bf16 v[60:63], v[172:175], v[188:191], v[60:63]
	v_mfma_f32_16x16x32_bf16 v[52:55], v[180:183], v[188:191], v[52:55]
	v_mfma_f32_16x16x32_bf16 v[44:47], v[172:175], v[196:199], v[44:47]
	v_mfma_f32_16x16x32_bf16 v[36:39], v[180:183], v[196:199], v[36:39]
	v_mfma_f32_16x16x32_bf16 v[28:31], v[172:175], v[204:207], v[28:31]
	v_mfma_f32_16x16x32_bf16 v[20:23], v[180:183], v[204:207], v[20:23]
	v_mfma_f32_16x16x32_bf16 v[12:15], v[172:175], v[226:229], v[12:15]
	v_mfma_f32_16x16x32_bf16 v[4:7], v[180:183], v[226:229], v[4:7]
	v_mfma_f32_16x16x32_bf16 v[60:63], v[176:179], v[192:195], v[60:63]
	v_mfma_f32_16x16x32_bf16 v[52:55], v[184:187], v[192:195], v[52:55]
	v_mfma_f32_16x16x32_bf16 v[44:47], v[176:179], v[200:203], v[44:47]
	v_mfma_f32_16x16x32_bf16 v[36:39], v[184:187], v[200:203], v[36:39]
	v_mfma_f32_16x16x32_bf16 v[28:31], v[176:179], v[208:211], v[28:31]
	v_mfma_f32_16x16x32_bf16 v[20:23], v[184:187], v[208:211], v[20:23]
	v_mfma_f32_16x16x32_bf16 v[12:15], v[176:179], v[230:233], v[12:15]
	v_mfma_f32_16x16x32_bf16 v[4:7], v[184:187], v[230:233], v[4:7]
	s_barrier
	s_add_i32 s47, 0, 0x18000
	s_add_i32 s48, 0, 0x1c000
	v_add_u32_e32 v142, s47, v147
	v_add_u32_e32 v156, s47, v148
	v_add_u32_e32 v164, s52, v148
	v_add_u32_e32 v168, s48, v147
	v_add_u32_e32 v176, s48, v148
	ds_read_b128 v[142:145], v142
	ds_read_b128 v[156:159], v156
	ds_read_b128 v[160:163], v155
	ds_read_b128 v[164:167], v164
	ds_read_b128 v[172:175], v168
	ds_read_b128 v[176:179], v176
	v_add_u32_e32 v168, s53, v147
	v_add_u32_e32 v184, s53, v148
	ds_read_b128 v[180:183], v168
	ds_read_b128 v[184:187], v184
	s_add_u32 s24, s24, 0x80000
	s_addc_u32 s25, s25, 0
	s_mov_b32 m0, s38
	v_lshl_add_u64 v[240:241], s[24:25], 0, v[136:137]
	ds_read_b128 v[188:191], v154 offset:32768
	ds_read_b128 v[192:195], v154 offset:33792
	ds_read_b128 v[196:199], v154 offset:34816
	ds_read_b128 v[200:203], v154 offset:35840
	ds_read_b128 v[204:207], v154 offset:36864
	ds_read_b128 v[208:211], v154 offset:37888
	ds_read_b128 v[226:229], v154 offset:38912
	ds_read_b128 v[230:233], v154 offset:39936
	global_load_lds_dwordx4 v[240:241], off
	v_lshl_add_u64 v[240:241], s[24:25], 0, v[134:135]
	s_mov_b32 m0, s39
	s_nop 0
	global_load_lds_dwordx4 v[240:241], off
	s_waitcnt vmcnt(8)
	s_waitcnt lgkmcnt(0)
	s_barrier
	v_mfma_f32_16x16x32_bf16 v[128:131], v[142:145], v[188:191], v[128:131]
	v_mfma_f32_16x16x32_bf16 v[120:123], v[160:163], v[188:191], v[120:123]
	v_mfma_f32_16x16x32_bf16 v[112:115], v[142:145], v[196:199], v[112:115]
	v_mfma_f32_16x16x32_bf16 v[104:107], v[160:163], v[196:199], v[104:107]
	v_mfma_f32_16x16x32_bf16 v[96:99], v[142:145], v[204:207], v[96:99]
	v_mfma_f32_16x16x32_bf16 v[88:91], v[160:163], v[204:207], v[88:91]
	v_mfma_f32_16x16x32_bf16 v[80:83], v[142:145], v[226:229], v[80:83]
	v_mfma_f32_16x16x32_bf16 v[72:75], v[160:163], v[226:229], v[72:75]
	v_mfma_f32_16x16x32_bf16 v[128:131], v[156:159], v[192:195], v[128:131]
	v_mfma_f32_16x16x32_bf16 v[120:123], v[164:167], v[192:195], v[120:123]
	v_mfma_f32_16x16x32_bf16 v[112:115], v[156:159], v[200:203], v[112:115]
	v_mfma_f32_16x16x32_bf16 v[104:107], v[164:167], v[200:203], v[104:107]
	v_mfma_f32_16x16x32_bf16 v[96:99], v[156:159], v[208:211], v[96:99]
	v_mfma_f32_16x16x32_bf16 v[88:91], v[164:167], v[208:211], v[88:91]
	v_mfma_f32_16x16x32_bf16 v[80:83], v[156:159], v[230:233], v[80:83]
	v_mfma_f32_16x16x32_bf16 v[72:75], v[164:167], v[230:233], v[72:75]
	v_mfma_f32_16x16x32_bf16 v[124:127], v[172:175], v[188:191], v[124:127]
	v_mfma_f32_16x16x32_bf16 v[116:119], v[180:183], v[188:191], v[116:119]
	v_mfma_f32_16x16x32_bf16 v[108:111], v[172:175], v[196:199], v[108:111]
	v_mfma_f32_16x16x32_bf16 v[100:103], v[180:183], v[196:199], v[100:103]
	v_mfma_f32_16x16x32_bf16 v[92:95], v[172:175], v[204:207], v[92:95]
	v_mfma_f32_16x16x32_bf16 v[84:87], v[180:183], v[204:207], v[84:87]
	v_mfma_f32_16x16x32_bf16 v[76:79], v[172:175], v[226:229], v[76:79]
	v_mfma_f32_16x16x32_bf16 v[68:71], v[180:183], v[226:229], v[68:71]
	v_mfma_f32_16x16x32_bf16 v[124:127], v[176:179], v[192:195], v[124:127]
	v_mfma_f32_16x16x32_bf16 v[116:119], v[184:187], v[192:195], v[116:119]
	v_mfma_f32_16x16x32_bf16 v[108:111], v[176:179], v[200:203], v[108:111]
	v_mfma_f32_16x16x32_bf16 v[100:103], v[184:187], v[200:203], v[100:103]
	v_mfma_f32_16x16x32_bf16 v[92:95], v[176:179], v[208:211], v[92:95]
	v_mfma_f32_16x16x32_bf16 v[84:87], v[184:187], v[208:211], v[84:87]
	v_mfma_f32_16x16x32_bf16 v[76:79], v[176:179], v[230:233], v[76:79]
	v_mfma_f32_16x16x32_bf16 v[68:71], v[184:187], v[230:233], v[68:71]
	s_barrier
; #define PG8_STAGE(bufoff, gbase, voff) do { _Pragma("unroll") for (int _i = 0; _i < 2; ++_i) \
;         __builtin_amdgcn_global_load_lds((const unsigned*)((const char*)(gbase) + (voff)[_i]), (PG8_LAS unsigned*)(lds + (bufoff) + ldsw + _i * 8192), 16, 0, 0); } while (0)
; #define PG8_LDA(dst, b, h) do { _Pragma("unroll") for (int m = 0; m < 4; ++m) _Pragma("unroll") for (int k = 0; k < 2; ++k) dst[m][k] = *(const PG8_LAS bf16x8*)(lds + PG8_SA(b, h) + aoffk[k] + m * 2048); } while (0)
; #define PG8_MMA(ai, bj, At, Bt) do { __builtin_amdgcn_s_setprio(1); _Pragma("unroll") for (int m = 0; m < 4; ++m) _Pragma("unroll") for (int n = 0; n < 2; ++n) _Pragma("unroll") for (int k = 0; k < 2; ++k) \
;         acc[ai][bj][m][n] = __builtin_amdgcn_mfma_f32_16x16x32_bf16(Bt[n][k], At[m][k], acc[ai][bj][m][n], 0, 0, 0); __builtin_amdgcn_s_setprio(0); } while (0)
; #define PG8_WAIT_V(n) asm volatile("s_waitcnt vmcnt(" #n ")" ::: "memory")
; #define PG8_WAIT_L(n) asm volatile("s_waitcnt lgkmcnt(" #n ")" ::: "memory")
; #define PG8_BAR __builtin_amdgcn_s_barrier()
; #define PG8_SCHED __builtin_amdgcn_sched_barrier(0)
; template <class Epi, class Sched, bool ALIGN_EPI = false, bool SP2 = false>
; __device__ __forceinline__ void gemm_phase(PG8_LAS unsigned char* lds, const Gemm g, const Sched& S, const Epi& E) {
;     ...
;             PG8_LDA(At, 1, 1); PG8_STAGE(PG8_SB(1, 0), b3, voffB); PG8_STAGE(PG8_SB(1, 1), b3 + hstepB, voffB); PG8_STAGE(PG8_SA(1, 0), a3, voffA);
;             PG8_WAIT_V(8); PG8_WAIT_L(0); PG8_BAR; PG8_MMA(1, 0, At, B0); PG8_MMA(1, 1, At, B1); PG8_BAR; PG8_SCHED;
	s_add_i32 s24, s47, s34
	v_lshl_add_u64 v[212:213], v[212:213], 0, s[56:57]
	s_mov_b32 m0, s24
	ds_read_b128 v[188:191], v154 offset:49152
	ds_read_b128 v[192:195], v154 offset:50176
	ds_read_b128 v[196:199], v154 offset:51200
	ds_read_b128 v[200:203], v154 offset:52224
	ds_read_b128 v[204:207], v154 offset:53248
	ds_read_b128 v[208:211], v154 offset:54272
	ds_read_b128 v[226:229], v154 offset:55296
	ds_read_b128 v[230:233], v154 offset:56320
	global_load_lds_dwordx4 v[212:213], off
	s_add_i32 m0, s24, 0x2000
	s_add_u32 s22, s22, 0x80080
	v_lshl_add_u64 v[212:213], v[234:235], 0, s[56:57]
	s_addc_u32 s23, s23, 0
	s_add_i32 s24, s48, s34
	global_load_lds_dwordx4 v[212:213], off
	v_lshl_add_u64 v[212:213], s[22:23], 0, v[2:3]
	s_mov_b32 m0, s24
	s_nop 0
	global_load_lds_dwordx4 v[212:213], off
	v_lshl_add_u64 v[212:213], s[22:23], 0, v[132:133]
	s_add_i32 m0, s24, 0x2000
	s_nop 0
	global_load_lds_dwordx4 v[212:213], off
	v_lshl_add_u64 v[212:213], v[236:237], 0, s[56:57]
	s_mov_b32 m0, s40
	s_nop 0
	global_load_lds_dwordx4 v[212:213], off
	v_lshl_add_u64 v[212:213], v[238:239], 0, s[56:57]
	s_mov_b32 m0, s41
	s_nop 0
	global_load_lds_dwordx4 v[212:213], off
	s_waitcnt vmcnt(8)
	s_waitcnt lgkmcnt(0)
	s_barrier
	v_mfma_f32_16x16x32_bf16 v[64:67], v[142:145], v[188:191], v[64:67]
	v_mfma_f32_16x16x32_bf16 v[56:59], v[160:163], v[188:191], v[56:59]
	v_mfma_f32_16x16x32_bf16 v[48:51], v[142:145], v[196:199], v[48:51]
	v_mfma_f32_16x16x32_bf16 v[40:43], v[160:163], v[196:199], v[40:43]
	v_mfma_f32_16x16x32_bf16 v[32:35], v[142:145], v[204:207], v[32:35]
	v_mfma_f32_16x16x32_bf16 v[24:27], v[160:163], v[204:207], v[24:27]
	v_mfma_f32_16x16x32_bf16 v[16:19], v[142:145], v[226:229], v[16:19]
	v_mfma_f32_16x16x32_bf16 v[8:11], v[160:163], v[226:229], v[8:11]
	v_mfma_f32_16x16x32_bf16 v[64:67], v[156:159], v[192:195], v[64:67]
	v_mfma_f32_16x16x32_bf16 v[56:59], v[164:167], v[192:195], v[56:59]
	v_mfma_f32_16x16x32_bf16 v[48:51], v[156:159], v[200:203], v[48:51]
	v_mfma_f32_16x16x32_bf16 v[40:43], v[164:167], v[200:203], v[40:43]
	v_mfma_f32_16x16x32_bf16 v[32:35], v[156:159], v[208:211], v[32:35]
	v_mfma_f32_16x16x32_bf16 v[24:27], v[164:167], v[208:211], v[24:27]
	v_mfma_f32_16x16x32_bf16 v[16:19], v[156:159], v[230:233], v[16:19]
	v_mfma_f32_16x16x32_bf16 v[8:11], v[164:167], v[230:233], v[8:11]
	v_mfma_f32_16x16x32_bf16 v[60:63], v[172:175], v[188:191], v[60:63]
	v_mfma_f32_16x16x32_bf16 v[52:55], v[180:183], v[188:191], v[52:55]
	v_mfma_f32_16x16x32_bf16 v[44:47], v[172:175], v[196:199], v[44:47]
	v_mfma_f32_16x16x32_bf16 v[36:39], v[180:183], v[196:199], v[36:39]
	v_mfma_f32_16x16x32_bf16 v[28:31], v[172:175], v[204:207], v[28:31]
	v_mfma_f32_16x16x32_bf16 v[20:23], v[180:183], v[204:207], v[20:23]
	v_mfma_f32_16x16x32_bf16 v[12:15], v[172:175], v[226:229], v[12:15]
	v_mfma_f32_16x16x32_bf16 v[4:7], v[180:183], v[226:229], v[4:7]
	v_mfma_f32_16x16x32_bf16 v[60:63], v[176:179], v[192:195], v[60:63]
	v_mfma_f32_16x16x32_bf16 v[52:55], v[184:187], v[192:195], v[52:55]
	v_mfma_f32_16x16x32_bf16 v[44:47], v[176:179], v[200:203], v[44:47]
	v_mfma_f32_16x16x32_bf16 v[36:39], v[184:187], v[200:203], v[36:39]
	v_mfma_f32_16x16x32_bf16 v[28:31], v[176:179], v[208:211], v[28:31]
	v_mfma_f32_16x16x32_bf16 v[20:23], v[184:187], v[208:211], v[20:23]
	v_mfma_f32_16x16x32_bf16 v[12:15], v[176:179], v[230:233], v[12:15]
	v_mfma_f32_16x16x32_bf16 v[4:7], v[184:187], v[230:233], v[4:7]
	s_barrier
	s_add_i32 s46, s46, 2
	s_add_u32 s20, s20, 0x100
	s_addc_u32 s21, s21, 0
	s_add_u32 s44, s44, 0x100
	s_addc_u32 s45, s45, 0
	s_cmp_gt_u32 s46, 29
	s_cbranch_scc0 .LBB0_296
	s_and_b64 vcc, exec, s[6:7]
	s_cbranch_vccz .LBB0_299
	s_barrier

; #define PG8_STAGE(bufoff, gbase, voff) do { _Pragma("unroll") for (int _i = 0; _i < 2; ++_i) \
;         __builtin_amdgcn_global_load_lds((const unsigned*)((const char*)(gbase) + (voff)[_i]), (PG8_LAS unsigned*)(lds + (bufoff) + ldsw + _i * 8192), 16, 0, 0); } while (0)
; #define PG8_LDA(dst, b, h) do { _Pragma("unroll") for (int m = 0; m < 4; ++m) _Pragma("unroll") for (int k = 0; k < 2; ++k) dst[m][k] = *(const PG8_LAS bf16x8*)(lds + PG8_SA(b, h) + aoffk[k] + m * 2048); } while (0)
; #define PG8_LDB(dst, b, h) do { _Pragma("unroll") for (int n = 0; n < 2; ++n) _Pragma("unroll") for (int k = 0; k < 2; ++k) dst[n][k] = *(const PG8_LAS bf16x8*)(lds + PG8_SB(b, h) + boffk[k] + n * 2048); } while (0)
; #define PG8_MMA(ai, bj, At, Bt) do { __builtin_amdgcn_s_setprio(1); _Pragma("unroll") for (int m = 0; m < 4; ++m) _Pragma("unroll") for (int n = 0; n < 2; ++n) _Pragma("unroll") for (int k = 0; k < 2; ++k) \
;         acc[ai][bj][m][n] = __builtin_amdgcn_mfma_f32_16x16x32_bf16(Bt[n][k], At[m][k], acc[ai][bj][m][n], 0, 0, 0); __builtin_amdgcn_s_setprio(0); } while (0)
; #define PG8_WAIT_V(n) asm volatile("s_waitcnt vmcnt(" #n ")" ::: "memory")
; #define PG8_WAIT_L(n) asm volatile("s_waitcnt lgkmcnt(" #n ")" ::: "memory")
; #define PG8_BAR __builtin_amdgcn_s_barrier()
; template <class Epi, class Sched, bool ALIGN_EPI = false, bool SP2 = false>
; __device__ __forceinline__ void gemm_phase(PG8_LAS unsigned char* lds, const Gemm g, const Sched& S, const Epi& E) {
;     ...
;             const bool last = (t == nt - 2);
;             const char* a1 = cA + (size_t)(t + 1) * kstep;
;             const char* a2 = last ? nA : cA + (size_t)(t + 2) * kstep; const char* b2 = last ? nB : cB + (size_t)(t + 2) * kstep;
;             const char* a3 = a2 + kstep; const char* b3 = b2 + kstep;
;             if (last && has_next) S.a_ready(nxt);
;             if constexpr (SP2) {
;             PG8_LDB(B0, 0, 0); PG8_LDB(B1, 0, 1); PG8_SCHED; PG8_LDA(At, 0, 0); PG8_STAGE(PG8_SA(1, 1), a1 + hstepA, voffA);
;             PG8_WAIT_V(8); PG8_WAIT_L(0); PG8_BAR; PG8_MMA(0, 0, At, B0); PG8_MMA(0, 1, At, B1); PG8_BAR; PG8_SCHED;
;             PG8_LDA(At, 0, 1); PG8_STAGE(PG8_SB(0, 0), b2, voffB); PG8_STAGE(PG8_SB(0, 1), b2 + hstepB, voffB); PG8_STAGE(PG8_SA(0, 0), a2, voffA);
;             PG8_WAIT_V(8); PG8_WAIT_L(0); PG8_BAR; PG8_MMA(1, 0, At, B0); PG8_MMA(1, 1, At, B1); PG8_BAR; PG8_SCHED;
.LBB0_430:
	s_add_i32 s51, s18, 2
	s_add_u32 s16, s14, 0x100
	s_addc_u32 s17, s15, 0
	s_add_i32 s52, 0, 0x10000
	s_cmp_eq_u32 s9, s18
	v_add_u32_e32 v142, s52, v145
	s_cselect_b32 s21, s11, s17
	s_cselect_b32 s20, s10, s16
	v_add_u32_e32 v143, s52, v146
	ds_read_b128 v[150:153], v142
	ds_read_b128 v[154:157], v143
	v_add_u32_e32 v142, s54, v145
	s_cselect_b32 s19, s13, s50
	s_cselect_b32 s18, s12, s49
	s_add_i32 s53, 0, 0x14000
	v_add_u32_e32 v143, s54, v146
	ds_read_b128 v[158:161], v142
	ds_read_b128 v[162:165], v143
	v_add_u32_e32 v142, s53, v145
	v_add_u32_e32 v143, s53, v146
	ds_read_b128 v[172:175], v142
	ds_read_b128 v[176:179], v143
	v_add_u32_e32 v142, s55, v145
	v_add_u32_e32 v143, s55, v146
	ds_read_b128 v[180:183], v142
	ds_read_b128 v[184:187], v143
	v_lshl_add_u64 v[142:143], s[14:15], 0, v[138:139]
	s_add_i32 m0, s28, 0xc000
	ds_read_b128 v[188:191], v148
	ds_read_b128 v[192:195], v148 offset:1024
	ds_read_b128 v[196:199], v148 offset:2048
	ds_read_b128 v[200:203], v148 offset:3072
	ds_read_b128 v[204:207], v148 offset:4096
	ds_read_b128 v[208:211], v148 offset:5120
	ds_read_b128 v[226:229], v148 offset:6144
	ds_read_b128 v[230:233], v148 offset:7168
	global_load_lds_dwordx4 v[142:143], off
	v_lshl_add_u64 v[142:143], s[14:15], 0, v[140:141]
	s_add_i32 m0, s28, 0xe000
	s_nop 0
	global_load_lds_dwordx4 v[142:143], off
	s_waitcnt vmcnt(8)
	s_waitcnt lgkmcnt(0)
	s_barrier
	v_mfma_f32_16x16x32_bf16 v[128:131], v[150:153], v[188:191], v[128:131]
	v_mfma_f32_16x16x32_bf16 v[124:127], v[158:161], v[188:191], v[124:127]
	v_mfma_f32_16x16x32_bf16 v[120:123], v[150:153], v[196:199], v[120:123]
	v_mfma_f32_16x16x32_bf16 v[112:115], v[158:161], v[196:199], v[112:115]
	v_mfma_f32_16x16x32_bf16 v[104:107], v[150:153], v[204:207], v[104:107]
	v_mfma_f32_16x16x32_bf16 v[96:99], v[158:161], v[204:207], v[96:99]
	v_mfma_f32_16x16x32_bf16 v[88:91], v[150:153], v[226:229], v[88:91]
	v_mfma_f32_16x16x32_bf16 v[80:83], v[158:161], v[226:229], v[80:83]
	v_mfma_f32_16x16x32_bf16 v[128:131], v[154:157], v[192:195], v[128:131]
	v_mfma_f32_16x16x32_bf16 v[124:127], v[162:165], v[192:195], v[124:127]
	v_mfma_f32_16x16x32_bf16 v[120:123], v[154:157], v[200:203], v[120:123]
	v_mfma_f32_16x16x32_bf16 v[112:115], v[162:165], v[200:203], v[112:115]
	v_mfma_f32_16x16x32_bf16 v[104:107], v[154:157], v[208:211], v[104:107]
	v_mfma_f32_16x16x32_bf16 v[96:99], v[162:165], v[208:211], v[96:99]
	v_mfma_f32_16x16x32_bf16 v[88:91], v[154:157], v[230:233], v[88:91]
	v_mfma_f32_16x16x32_bf16 v[80:83], v[162:165], v[230:233], v[80:83]
	v_mfma_f32_16x16x32_bf16 v[116:119], v[172:175], v[188:191], v[116:119]
	v_mfma_f32_16x16x32_bf16 v[108:111], v[180:183], v[188:191], v[108:111]
	v_mfma_f32_16x16x32_bf16 v[100:103], v[172:175], v[196:199], v[100:103]
	v_mfma_f32_16x16x32_bf16 v[92:95], v[180:183], v[196:199], v[92:95]
	v_mfma_f32_16x16x32_bf16 v[84:87], v[172:175], v[204:207], v[84:87]
	v_mfma_f32_16x16x32_bf16 v[76:79], v[180:183], v[204:207], v[76:79]
	v_mfma_f32_16x16x32_bf16 v[72:75], v[172:175], v[226:229], v[72:75]
	v_mfma_f32_16x16x32_bf16 v[68:71], v[180:183], v[226:229], v[68:71]
	v_mfma_f32_16x16x32_bf16 v[116:119], v[176:179], v[192:195], v[116:119]
	v_mfma_f32_16x16x32_bf16 v[108:111], v[184:187], v[192:195], v[108:111]
	v_mfma_f32_16x16x32_bf16 v[100:103], v[176:179], v[200:203], v[100:103]
	v_mfma_f32_16x16x32_bf16 v[92:95], v[184:187], v[200:203], v[92:95]
	v_mfma_f32_16x16x32_bf16 v[84:87], v[176:179], v[208:211], v[84:87]
	v_mfma_f32_16x16x32_bf16 v[76:79], v[184:187], v[208:211], v[76:79]
	v_mfma_f32_16x16x32_bf16 v[72:75], v[176:179], v[230:233], v[72:75]
	v_mfma_f32_16x16x32_bf16 v[68:71], v[184:187], v[230:233], v[68:71]
	s_barrier
	s_add_i32 s14, s52, s27
	v_lshl_add_u64 v[142:143], s[18:19], 0, v[2:3]
	s_mov_b32 m0, s14
	ds_read_b128 v[188:191], v148 offset:16384
	ds_read_b128 v[192:195], v148 offset:17408
	ds_read_b128 v[196:199], v148 offset:18432
	ds_read_b128 v[200:203], v148 offset:19456
	ds_read_b128 v[204:207], v148 offset:20480
	ds_read_b128 v[208:211], v148 offset:21504
	ds_read_b128 v[226:229], v148 offset:22528
	ds_read_b128 v[230:233], v148 offset:23552
	global_load_lds_dwordx4 v[142:143], off
	s_add_i32 m0, s14, 0x2000
	s_add_u32 s14, s18, 0x160000
	v_lshl_add_u64 v[166:167], s[18:19], 0, v[136:137]
	s_addc_u32 s15, s19, 0
	s_add_i32 s52, s53, s27
	global_load_lds_dwordx4 v[166:167], off
	v_lshl_add_u64 v[212:213], s[14:15], 0, v[2:3]
	s_mov_b32 m0, s52
	v_lshl_add_u64 v[234:235], s[20:21], 0, v[134:135]
	global_load_lds_dwordx4 v[212:213], off
	v_lshl_add_u64 v[212:213], s[14:15], 0, v[136:137]
	s_add_i32 m0, s52, 0x2000
	s_nop 0
	global_load_lds_dwordx4 v[212:213], off
	v_lshl_add_u64 v[212:213], s[20:21], 0, v[132:133]
	s_mov_b32 m0, s28
	s_nop 0
	global_load_lds_dwordx4 v[212:213], off
	s_mov_b32 m0, s29
	s_nop 0
	global_load_lds_dwordx4 v[234:235], off
	s_waitcnt vmcnt(8)
	s_waitcnt lgkmcnt(0)
	s_barrier
; #define PG8_STAGE(bufoff, gbase, voff) do { _Pragma("unroll") for (int _i = 0; _i < 2; ++_i) \
;         __builtin_amdgcn_global_load_lds((const unsigned*)((const char*)(gbase) + (voff)[_i]), (PG8_LAS unsigned*)(lds + (bufoff) + ldsw + _i * 8192), 16, 0, 0); } while (0)
; #define PG8_LDA(dst, b, h) do { _Pragma("unroll") for (int m = 0; m < 4; ++m) _Pragma("unroll") for (int k = 0; k < 2; ++k) dst[m][k] = *(const PG8_LAS bf16x8*)(lds + PG8_SA(b, h) + aoffk[k] + m * 2048); } while (0)
; #define PG8_LDB(dst, b, h) do { _Pragma("unroll") for (int n = 0; n < 2; ++n) _Pragma("unroll") for (int k = 0; k < 2; ++k) dst[n][k] = *(const PG8_LAS bf16x8*)(lds + PG8_SB(b, h) + boffk[k] + n * 2048); } while (0)
; #define PG8_MMA(ai, bj, At, Bt) do { __builtin_amdgcn_s_setprio(1); _Pragma("unroll") for (int m = 0; m < 4; ++m) _Pragma("unroll") for (int n = 0; n < 2; ++n) _Pragma("unroll") for (int k = 0; k < 2; ++k) \
;         acc[ai][bj][m][n] = __builtin_amdgcn_mfma_f32_16x16x32_bf16(Bt[n][k], At[m][k], acc[ai][bj][m][n], 0, 0, 0); __builtin_amdgcn_s_setprio(0); } while (0)
; #define PG8_WAIT_V(n) asm volatile("s_waitcnt vmcnt(" #n ")" ::: "memory")
; #define PG8_WAIT_L(n) asm volatile("s_waitcnt lgkmcnt(" #n ")" ::: "memory")
; #define PG8_BAR __builtin_amdgcn_s_barrier()
; #define PG8_SCHED __builtin_amdgcn_sched_barrier(0)
; template <class Epi, class Sched, bool ALIGN_EPI = false, bool SP2 = false>
; __device__ __forceinline__ void gemm_phase(PG8_LAS unsigned char* lds, const Gemm g, const Sched& S, const Epi& E) {
;     ...
;             PG8_WAIT_V(8); PG8_WAIT_L(0); PG8_BAR; PG8_MMA(1, 0, At, B0); PG8_MMA(1, 1, At, B1); PG8_BAR; PG8_SCHED;
;             PG8_LDB(B0, 1, 0); PG8_LDB(B1, 1, 1); PG8_SCHED; PG8_LDA(At, 1, 0); PG8_STAGE(PG8_SA(0, 1), a2 + hstepA, voffA);
;             PG8_WAIT_V(8); PG8_WAIT_L(0); PG8_BAR; PG8_MMA(0, 0, At, B0); PG8_MMA(0, 1, At, B1); PG8_BAR; PG8_SCHED;
	v_mfma_f32_16x16x32_bf16 v[64:67], v[150:153], v[188:191], v[64:67]
	v_mfma_f32_16x16x32_bf16 v[60:63], v[158:161], v[188:191], v[60:63]
	v_mfma_f32_16x16x32_bf16 v[56:59], v[150:153], v[196:199], v[56:59]
	v_mfma_f32_16x16x32_bf16 v[48:51], v[158:161], v[196:199], v[48:51]
	v_mfma_f32_16x16x32_bf16 v[40:43], v[150:153], v[204:207], v[40:43]
	v_mfma_f32_16x16x32_bf16 v[32:35], v[158:161], v[204:207], v[32:35]
	v_mfma_f32_16x16x32_bf16 v[24:27], v[150:153], v[226:229], v[24:27]
	v_mfma_f32_16x16x32_bf16 v[16:19], v[158:161], v[226:229], v[16:19]
	v_mfma_f32_16x16x32_bf16 v[64:67], v[154:157], v[192:195], v[64:67]
	v_mfma_f32_16x16x32_bf16 v[60:63], v[162:165], v[192:195], v[60:63]
	v_mfma_f32_16x16x32_bf16 v[56:59], v[154:157], v[200:203], v[56:59]
	v_mfma_f32_16x16x32_bf16 v[48:51], v[162:165], v[200:203], v[48:51]
	v_mfma_f32_16x16x32_bf16 v[40:43], v[154:157], v[208:211], v[40:43]
	v_mfma_f32_16x16x32_bf16 v[32:35], v[162:165], v[208:211], v[32:35]
	v_mfma_f32_16x16x32_bf16 v[24:27], v[154:157], v[230:233], v[24:27]
	v_mfma_f32_16x16x32_bf16 v[16:19], v[162:165], v[230:233], v[16:19]
	v_mfma_f32_16x16x32_bf16 v[52:55], v[172:175], v[188:191], v[52:55]
	v_mfma_f32_16x16x32_bf16 v[44:47], v[180:183], v[188:191], v[44:47]
	v_mfma_f32_16x16x32_bf16 v[36:39], v[172:175], v[196:199], v[36:39]
	v_mfma_f32_16x16x32_bf16 v[28:31], v[180:183], v[196:199], v[28:31]
	v_mfma_f32_16x16x32_bf16 v[20:23], v[172:175], v[204:207], v[20:23]
	v_mfma_f32_16x16x32_bf16 v[12:15], v[180:183], v[204:207], v[12:15]
	v_mfma_f32_16x16x32_bf16 v[8:11], v[172:175], v[226:229], v[8:11]
	v_mfma_f32_16x16x32_bf16 v[4:7], v[180:183], v[226:229], v[4:7]
	v_mfma_f32_16x16x32_bf16 v[52:55], v[176:179], v[192:195], v[52:55]
	v_mfma_f32_16x16x32_bf16 v[44:47], v[184:187], v[192:195], v[44:47]
	v_mfma_f32_16x16x32_bf16 v[36:39], v[176:179], v[200:203], v[36:39]
	v_mfma_f32_16x16x32_bf16 v[28:31], v[184:187], v[200:203], v[28:31]
	v_mfma_f32_16x16x32_bf16 v[20:23], v[176:179], v[208:211], v[20:23]
	v_mfma_f32_16x16x32_bf16 v[12:15], v[184:187], v[208:211], v[12:15]
	v_mfma_f32_16x16x32_bf16 v[8:11], v[176:179], v[230:233], v[8:11]
	v_mfma_f32_16x16x32_bf16 v[4:7], v[184:187], v[230:233], v[4:7]
	s_barrier
	s_add_i32 s52, 0, 0x18000
	v_add_u32_e32 v149, s52, v145
	v_add_u32_e32 v154, s52, v146
	ds_read_b128 v[150:153], v149
	ds_read_b128 v[154:157], v154
	v_add_u32_e32 v149, s56, v145
	v_add_u32_e32 v162, s56, v146
	s_add_i32 s53, 0, 0x1c000
	ds_read_b128 v[158:161], v149
	ds_read_b128 v[162:165], v162
	v_add_u32_e32 v149, s53, v145
	v_add_u32_e32 v168, s53, v146
	ds_read_b128 v[172:175], v149
	ds_read_b128 v[176:179], v168
	v_add_u32_e32 v149, s57, v145
	v_add_u32_e32 v168, s57, v146
	ds_read_b128 v[180:183], v149
	ds_read_b128 v[184:187], v168
	s_add_u32 s14, s20, 0x160000
	s_addc_u32 s15, s21, 0
	s_mov_b32 m0, s30
	v_lshl_add_u64 v[236:237], s[14:15], 0, v[132:133]
	ds_read_b128 v[188:191], v148 offset:32768
	ds_read_b128 v[192:195], v148 offset:33792
	ds_read_b128 v[196:199], v148 offset:34816
	ds_read_b128 v[200:203], v148 offset:35840
	ds_read_b128 v[204:207], v148 offset:36864
	ds_read_b128 v[208:211], v148 offset:37888
	ds_read_b128 v[226:229], v148 offset:38912
	ds_read_b128 v[230:233], v148 offset:39936
	global_load_lds_dwordx4 v[236:237], off
	v_lshl_add_u64 v[236:237], s[14:15], 0, v[134:135]
	s_mov_b32 m0, s31
	s_nop 0
	global_load_lds_dwordx4 v[236:237], off
	s_waitcnt vmcnt(8)
	s_waitcnt lgkmcnt(0)
	s_barrier
	v_mfma_f32_16x16x32_bf16 v[128:131], v[150:153], v[188:191], v[128:131]
	v_mfma_f32_16x16x32_bf16 v[124:127], v[158:161], v[188:191], v[124:127]
	v_mfma_f32_16x16x32_bf16 v[120:123], v[150:153], v[196:199], v[120:123]
	v_mfma_f32_16x16x32_bf16 v[112:115], v[158:161], v[196:199], v[112:115]
	v_mfma_f32_16x16x32_bf16 v[104:107], v[150:153], v[204:207], v[104:107]
	v_mfma_f32_16x16x32_bf16 v[96:99], v[158:161], v[204:207], v[96:99]
	v_mfma_f32_16x16x32_bf16 v[88:91], v[150:153], v[226:229], v[88:91]
	v_mfma_f32_16x16x32_bf16 v[80:83], v[158:161], v[226:229], v[80:83]
	v_mfma_f32_16x16x32_bf16 v[128:131], v[154:157], v[192:195], v[128:131]
	v_mfma_f32_16x16x32_bf16 v[124:127], v[162:165], v[192:195], v[124:127]
	v_mfma_f32_16x16x32_bf16 v[120:123], v[154:157], v[200:203], v[120:123]
	v_mfma_f32_16x16x32_bf16 v[112:115], v[162:165], v[200:203], v[112:115]
	v_mfma_f32_16x16x32_bf16 v[104:107], v[154:157], v[208:211], v[104:107]
	v_mfma_f32_16x16x32_bf16 v[96:99], v[162:165], v[208:211], v[96:99]
	v_mfma_f32_16x16x32_bf16 v[88:91], v[154:157], v[230:233], v[88:91]
	v_mfma_f32_16x16x32_bf16 v[80:83], v[162:165], v[230:233], v[80:83]
	v_mfma_f32_16x16x32_bf16 v[116:119], v[172:175], v[188:191], v[116:119]
	v_mfma_f32_16x16x32_bf16 v[108:111], v[180:183], v[188:191], v[108:111]
	v_mfma_f32_16x16x32_bf16 v[100:103], v[172:175], v[196:199], v[100:103]
	v_mfma_f32_16x16x32_bf16 v[92:95], v[180:183], v[196:199], v[92:95]
	v_mfma_f32_16x16x32_bf16 v[84:87], v[172:175], v[204:207], v[84:87]
	v_mfma_f32_16x16x32_bf16 v[76:79], v[180:183], v[204:207], v[76:79]
	v_mfma_f32_16x16x32_bf16 v[72:75], v[172:175], v[226:229], v[72:75]
	v_mfma_f32_16x16x32_bf16 v[68:71], v[180:183], v[226:229], v[68:71]
	v_mfma_f32_16x16x32_bf16 v[116:119], v[176:179], v[192:195], v[116:119]
	v_mfma_f32_16x16x32_bf16 v[108:111], v[184:187], v[192:195], v[108:111]
	v_mfma_f32_16x16x32_bf16 v[100:103], v[176:179], v[200:203], v[100:103]
	v_mfma_f32_16x16x32_bf16 v[92:95], v[184:187], v[200:203], v[92:95]
	v_mfma_f32_16x16x32_bf16 v[84:87], v[176:179], v[208:211], v[84:87]
	v_mfma_f32_16x16x32_bf16 v[76:79], v[184:187], v[208:211], v[76:79]
	v_mfma_f32_16x16x32_bf16 v[72:75], v[176:179], v[230:233], v[72:75]
	v_mfma_f32_16x16x32_bf16 v[68:71], v[184:187], v[230:233], v[68:71]
	s_barrier
; #define PG8_STAGE(bufoff, gbase, voff) do { _Pragma("unroll") for (int _i = 0; _i < 2; ++_i) \
;         __builtin_amdgcn_global_load_lds((const unsigned*)((const char*)(gbase) + (voff)[_i]), (PG8_LAS unsigned*)(lds + (bufoff) + ldsw + _i * 8192), 16, 0, 0); } while (0)
; #define PG8_LDA(dst, b, h) do { _Pragma("unroll") for (int m = 0; m < 4; ++m) _Pragma("unroll") for (int k = 0; k < 2; ++k) dst[m][k] = *(const PG8_LAS bf16x8*)(lds + PG8_SA(b, h) + aoffk[k] + m * 2048); } while (0)
; #define PG8_MMA(ai, bj, At, Bt) do { __builtin_amdgcn_s_setprio(1); _Pragma("unroll") for (int m = 0; m < 4; ++m) _Pragma("unroll") for (int n = 0; n < 2; ++n) _Pragma("unroll") for (int k = 0; k < 2; ++k) \
;         acc[ai][bj][m][n] = __builtin_amdgcn_mfma_f32_16x16x32_bf16(Bt[n][k], At[m][k], acc[ai][bj][m][n], 0, 0, 0); __builtin_amdgcn_s_setprio(0); } while (0)
; #define PG8_WAIT_V(n) asm volatile("s_waitcnt vmcnt(" #n ")" ::: "memory")
; #define PG8_WAIT_L(n) asm volatile("s_waitcnt lgkmcnt(" #n ")" ::: "memory")
; #define PG8_BAR __builtin_amdgcn_s_barrier()
; #define PG8_SCHED __builtin_amdgcn_sched_barrier(0)
; template <class Epi, class Sched, bool ALIGN_EPI = false, bool SP2 = false>
; __device__ __forceinline__ void gemm_phase(PG8_LAS unsigned char* lds, const Gemm g, const Sched& S, const Epi& E) {
;     ...
;             PG8_LDA(At, 1, 1); PG8_STAGE(PG8_SB(1, 0), b3, voffB); PG8_STAGE(PG8_SB(1, 1), b3 + hstepB, voffB); PG8_STAGE(PG8_SA(1, 0), a3, voffA);
;             PG8_WAIT_V(8); PG8_WAIT_L(0); PG8_BAR; PG8_MMA(1, 0, At, B0); PG8_MMA(1, 1, At, B1); PG8_BAR; PG8_SCHED;
	s_add_i32 s14, s52, s27
	v_lshl_add_u64 v[142:143], v[142:143], 0, s[58:59]
	s_mov_b32 m0, s14
	ds_read_b128 v[188:191], v148 offset:49152
	ds_read_b128 v[192:195], v148 offset:50176
	ds_read_b128 v[196:199], v148 offset:51200
	ds_read_b128 v[200:203], v148 offset:52224
	ds_read_b128 v[204:207], v148 offset:53248
	ds_read_b128 v[208:211], v148 offset:54272
	ds_read_b128 v[226:229], v148 offset:55296
	ds_read_b128 v[230:233], v148 offset:56320
	global_load_lds_dwordx4 v[142:143], off
	s_add_i32 m0, s14, 0x2000
	s_add_u32 s14, s18, 0x160080
	v_lshl_add_u64 v[142:143], v[166:167], 0, s[58:59]
	s_addc_u32 s15, s19, 0
	s_add_i32 s18, s53, s27
	global_load_lds_dwordx4 v[142:143], off
	v_lshl_add_u64 v[142:143], s[14:15], 0, v[2:3]
	s_mov_b32 m0, s18
	s_nop 0
	global_load_lds_dwordx4 v[142:143], off
	v_lshl_add_u64 v[142:143], s[14:15], 0, v[136:137]
	s_add_i32 m0, s18, 0x2000
	s_nop 0
	global_load_lds_dwordx4 v[142:143], off
	v_lshl_add_u64 v[142:143], v[212:213], 0, s[58:59]
	s_mov_b32 m0, s38
	s_nop 0
	global_load_lds_dwordx4 v[142:143], off
	v_lshl_add_u64 v[142:143], v[234:235], 0, s[58:59]
	s_mov_b32 m0, s39
	s_nop 0
	global_load_lds_dwordx4 v[142:143], off
	s_waitcnt vmcnt(8)
	s_waitcnt lgkmcnt(0)
	s_barrier
	v_mfma_f32_16x16x32_bf16 v[64:67], v[150:153], v[188:191], v[64:67]
	v_mfma_f32_16x16x32_bf16 v[60:63], v[158:161], v[188:191], v[60:63]
	v_mfma_f32_16x16x32_bf16 v[56:59], v[150:153], v[196:199], v[56:59]
	v_mfma_f32_16x16x32_bf16 v[48:51], v[158:161], v[196:199], v[48:51]
	v_mfma_f32_16x16x32_bf16 v[40:43], v[150:153], v[204:207], v[40:43]
	v_mfma_f32_16x16x32_bf16 v[32:35], v[158:161], v[204:207], v[32:35]
	v_mfma_f32_16x16x32_bf16 v[24:27], v[150:153], v[226:229], v[24:27]
	v_mfma_f32_16x16x32_bf16 v[16:19], v[158:161], v[226:229], v[16:19]
	v_mfma_f32_16x16x32_bf16 v[64:67], v[154:157], v[192:195], v[64:67]
	v_mfma_f32_16x16x32_bf16 v[60:63], v[162:165], v[192:195], v[60:63]
	v_mfma_f32_16x16x32_bf16 v[56:59], v[154:157], v[200:203], v[56:59]
	v_mfma_f32_16x16x32_bf16 v[48:51], v[162:165], v[200:203], v[48:51]
	v_mfma_f32_16x16x32_bf16 v[40:43], v[154:157], v[208:211], v[40:43]
	v_mfma_f32_16x16x32_bf16 v[32:35], v[162:165], v[208:211], v[32:35]
	v_mfma_f32_16x16x32_bf16 v[24:27], v[154:157], v[230:233], v[24:27]
	v_mfma_f32_16x16x32_bf16 v[16:19], v[162:165], v[230:233], v[16:19]
	v_mfma_f32_16x16x32_bf16 v[52:55], v[172:175], v[188:191], v[52:55]
	v_mfma_f32_16x16x32_bf16 v[44:47], v[180:183], v[188:191], v[44:47]
	v_mfma_f32_16x16x32_bf16 v[36:39], v[172:175], v[196:199], v[36:39]
	v_mfma_f32_16x16x32_bf16 v[28:31], v[180:183], v[196:199], v[28:31]
	v_mfma_f32_16x16x32_bf16 v[20:23], v[172:175], v[204:207], v[20:23]
	v_mfma_f32_16x16x32_bf16 v[12:15], v[180:183], v[204:207], v[12:15]
	v_mfma_f32_16x16x32_bf16 v[8:11], v[172:175], v[226:229], v[8:11]
	v_mfma_f32_16x16x32_bf16 v[4:7], v[180:183], v[226:229], v[4:7]
	v_mfma_f32_16x16x32_bf16 v[52:55], v[176:179], v[192:195], v[52:55]
	v_mfma_f32_16x16x32_bf16 v[44:47], v[184:187], v[192:195], v[44:47]
	v_mfma_f32_16x16x32_bf16 v[36:39], v[176:179], v[200:203], v[36:39]
	v_mfma_f32_16x16x32_bf16 v[28:31], v[184:187], v[200:203], v[28:31]
	v_mfma_f32_16x16x32_bf16 v[20:23], v[176:179], v[208:211], v[20:23]
	v_mfma_f32_16x16x32_bf16 v[12:15], v[184:187], v[208:211], v[12:15]
	v_mfma_f32_16x16x32_bf16 v[8:11], v[176:179], v[230:233], v[8:11]
	v_mfma_f32_16x16x32_bf16 v[4:7], v[184:187], v[230:233], v[4:7]
	s_barrier
	s_add_u32 s49, s49, 0x100
	s_addc_u32 s50, s50, 0
	s_cmp_ge_i32 s51, s44
	s_mov_b64 s[14:15], s[16:17]
	s_mov_b32 s18, s51
	s_cbranch_scc0 .LBB0_430
	s_and_b64 vcc, exec, s[6:7]
	s_cbranch_vccz .LBB0_433
	s_barrier

; #define PG8_STAGE(bufoff, gbase, voff) do { _Pragma("unroll") for (int _i = 0; _i < 2; ++_i) \
;         __builtin_amdgcn_global_load_lds((const unsigned*)((const char*)(gbase) + (voff)[_i]), (PG8_LAS unsigned*)(lds + (bufoff) + ldsw + _i * 8192), 16, 0, 0); } while (0)
; #define PG8_LDA(dst, b, h) do { _Pragma("unroll") for (int m = 0; m < 4; ++m) _Pragma("unroll") for (int k = 0; k < 2; ++k) dst[m][k] = *(const PG8_LAS bf16x8*)(lds + PG8_SA(b, h) + aoffk[k] + m * 2048); } while (0)
; #define PG8_LDB(dst, b, h) do { _Pragma("unroll") for (int n = 0; n < 2; ++n) _Pragma("unroll") for (int k = 0; k < 2; ++k) dst[n][k] = *(const PG8_LAS bf16x8*)(lds + PG8_SB(b, h) + boffk[k] + n * 2048); } while (0)
; #define PG8_MMA(ai, bj, At, Bt) do { __builtin_amdgcn_s_setprio(1); _Pragma("unroll") for (int m = 0; m < 4; ++m) _Pragma("unroll") for (int n = 0; n < 2; ++n) _Pragma("unroll") for (int k = 0; k < 2; ++k) \
;         acc[ai][bj][m][n] = __builtin_amdgcn_mfma_f32_16x16x32_bf16(Bt[n][k], At[m][k], acc[ai][bj][m][n], 0, 0, 0); __builtin_amdgcn_s_setprio(0); } while (0)
; #define PG8_WAIT_V(n) asm volatile("s_waitcnt vmcnt(" #n ")" ::: "memory")
; #define PG8_WAIT_L(n) asm volatile("s_waitcnt lgkmcnt(" #n ")" ::: "memory")
; #define PG8_BAR __builtin_amdgcn_s_barrier()
; template <class Epi, class Sched, bool ALIGN_EPI = false, bool SP2 = false>
; __device__ __forceinline__ void gemm_phase(PG8_LAS unsigned char* lds, const Gemm g, const Sched& S, const Epi& E) {
;     ...
;             const bool last = (t == nt - 2);
;             const char* a1 = cA + (size_t)(t + 1) * kstep;
;             const char* a2 = last ? nA : cA + (size_t)(t + 2) * kstep; const char* b2 = last ? nB : cB + (size_t)(t + 2) * kstep;
;             const char* a3 = a2 + kstep; const char* b3 = b2 + kstep;
;             if (last && has_next) S.a_ready(nxt);
;             if constexpr (SP2) {
;             PG8_LDB(B0, 0, 0); PG8_LDB(B1, 0, 1); PG8_SCHED; PG8_LDA(At, 0, 0); PG8_STAGE(PG8_SA(1, 1), a1 + hstepA, voffA);
;             PG8_WAIT_V(8); PG8_WAIT_L(0); PG8_BAR; PG8_MMA(0, 0, At, B0); PG8_MMA(0, 1, At, B1); PG8_BAR; PG8_SCHED;
;             PG8_LDA(At, 0, 1); PG8_STAGE(PG8_SB(0, 0), b2, voffB); PG8_STAGE(PG8_SB(0, 1), b2 + hstepB, voffB); PG8_STAGE(PG8_SA(0, 0), a2, voffA);
;             PG8_WAIT_V(8); PG8_WAIT_L(0); PG8_BAR; PG8_MMA(1, 0, At, B0); PG8_MMA(1, 1, At, B1); PG8_BAR; PG8_SCHED;
.LBB0_663:
	s_add_u32 s20, s18, 0xfff80080
	s_addc_u32 s21, s19, -1
	s_add_i32 s45, 0, 0x10000
	s_cmp_eq_u32 s44, 28
	v_add_u32_e32 v142, s45, v147
	v_add_u32_e32 v151, s45, v148
	s_cselect_b32 s23, s9, s21
	s_cselect_b32 s22, s40, s20
	ds_read_b128 v[142:145], v142
	ds_read_b128 v[152:155], v151
	v_add_u32_e32 v151, s49, v147
	v_add_u32_e32 v160, s49, v148
	s_cselect_b32 s21, s7, s43
	s_cselect_b32 s20, s41, s42
	s_add_i32 s48, 0, 0x14000
	ds_read_b128 v[156:159], v151
	ds_read_b128 v[160:163], v160
	v_add_u32_e32 v151, s48, v147
	v_add_u32_e32 v168, s48, v148
	ds_read_b128 v[164:167], v151
	ds_read_b128 v[172:175], v168
	v_add_u32_e32 v151, s50, v147
	v_add_u32_e32 v168, s50, v148
	ds_read_b128 v[176:179], v151
	ds_read_b128 v[180:183], v168
	v_lshl_add_u64 v[212:213], s[18:19], 0, v[138:139]
	s_add_i32 m0, s33, 0xc000
	ds_read_b128 v[184:187], v150
	ds_read_b128 v[188:191], v150 offset:1024
	ds_read_b128 v[192:195], v150 offset:2048
	ds_read_b128 v[196:199], v150 offset:3072
	ds_read_b128 v[200:203], v150 offset:4096
	ds_read_b128 v[204:207], v150 offset:5120
	ds_read_b128 v[208:211], v150 offset:6144
	ds_read_b128 v[226:229], v150 offset:7168
	global_load_lds_dwordx4 v[212:213], off
	v_lshl_add_u64 v[212:213], s[18:19], 0, v[140:141]
	s_add_i32 m0, s33, 0xe000
	s_nop 0
	global_load_lds_dwordx4 v[212:213], off
	s_waitcnt vmcnt(8)
	s_waitcnt lgkmcnt(0)
	s_barrier
	v_mfma_f32_16x16x32_bf16 v[128:131], v[142:145], v[184:187], v[128:131]
	v_mfma_f32_16x16x32_bf16 v[124:127], v[156:159], v[184:187], v[124:127]
	v_mfma_f32_16x16x32_bf16 v[120:123], v[142:145], v[192:195], v[120:123]
	v_mfma_f32_16x16x32_bf16 v[112:115], v[156:159], v[192:195], v[112:115]
	v_mfma_f32_16x16x32_bf16 v[104:107], v[142:145], v[200:203], v[104:107]
	v_mfma_f32_16x16x32_bf16 v[96:99], v[156:159], v[200:203], v[96:99]
	v_mfma_f32_16x16x32_bf16 v[88:91], v[142:145], v[208:211], v[88:91]
	v_mfma_f32_16x16x32_bf16 v[80:83], v[156:159], v[208:211], v[80:83]
	v_mfma_f32_16x16x32_bf16 v[128:131], v[152:155], v[188:191], v[128:131]
	v_mfma_f32_16x16x32_bf16 v[124:127], v[160:163], v[188:191], v[124:127]
	v_mfma_f32_16x16x32_bf16 v[120:123], v[152:155], v[196:199], v[120:123]
	v_mfma_f32_16x16x32_bf16 v[112:115], v[160:163], v[196:199], v[112:115]
	v_mfma_f32_16x16x32_bf16 v[104:107], v[152:155], v[204:207], v[104:107]
	v_mfma_f32_16x16x32_bf16 v[96:99], v[160:163], v[204:207], v[96:99]
	v_mfma_f32_16x16x32_bf16 v[88:91], v[152:155], v[226:229], v[88:91]
	v_mfma_f32_16x16x32_bf16 v[80:83], v[160:163], v[226:229], v[80:83]
	v_mfma_f32_16x16x32_bf16 v[116:119], v[164:167], v[184:187], v[116:119]
	v_mfma_f32_16x16x32_bf16 v[108:111], v[176:179], v[184:187], v[108:111]
	v_mfma_f32_16x16x32_bf16 v[100:103], v[164:167], v[192:195], v[100:103]
	v_mfma_f32_16x16x32_bf16 v[92:95], v[176:179], v[192:195], v[92:95]
	v_mfma_f32_16x16x32_bf16 v[84:87], v[164:167], v[200:203], v[84:87]
	v_mfma_f32_16x16x32_bf16 v[76:79], v[176:179], v[200:203], v[76:79]
	v_mfma_f32_16x16x32_bf16 v[72:75], v[164:167], v[208:211], v[72:75]
	v_mfma_f32_16x16x32_bf16 v[68:71], v[176:179], v[208:211], v[68:71]
	v_mfma_f32_16x16x32_bf16 v[116:119], v[172:175], v[188:191], v[116:119]
	v_mfma_f32_16x16x32_bf16 v[108:111], v[180:183], v[188:191], v[108:111]
	v_mfma_f32_16x16x32_bf16 v[100:103], v[172:175], v[196:199], v[100:103]
	v_mfma_f32_16x16x32_bf16 v[92:95], v[180:183], v[196:199], v[92:95]
	v_mfma_f32_16x16x32_bf16 v[84:87], v[172:175], v[204:207], v[84:87]
	v_mfma_f32_16x16x32_bf16 v[76:79], v[180:183], v[204:207], v[76:79]
	v_mfma_f32_16x16x32_bf16 v[72:75], v[172:175], v[226:229], v[72:75]
	v_mfma_f32_16x16x32_bf16 v[68:71], v[180:183], v[226:229], v[68:71]
	s_barrier
	s_add_i32 s45, s45, s30
	v_lshl_add_u64 v[212:213], s[20:21], 0, v[2:3]
	s_mov_b32 m0, s45
	ds_read_b128 v[184:187], v150 offset:16384
	ds_read_b128 v[188:191], v150 offset:17408
	ds_read_b128 v[192:195], v150 offset:18432
	ds_read_b128 v[196:199], v150 offset:19456
	ds_read_b128 v[200:203], v150 offset:20480
	ds_read_b128 v[204:207], v150 offset:21504
	ds_read_b128 v[208:211], v150 offset:22528
	ds_read_b128 v[226:229], v150 offset:23552
	global_load_lds_dwordx4 v[212:213], off
	s_add_i32 m0, s45, 0x2000
	s_add_u32 s46, s20, 0x80000
	v_lshl_add_u64 v[230:231], s[20:21], 0, v[132:133]
	s_addc_u32 s47, s21, 0
	s_add_i32 s45, s48, s30
	global_load_lds_dwordx4 v[230:231], off
	v_lshl_add_u64 v[232:233], s[46:47], 0, v[2:3]
	s_mov_b32 m0, s45
	v_lshl_add_u64 v[234:235], s[22:23], 0, v[134:135]
	global_load_lds_dwordx4 v[232:233], off
	v_lshl_add_u64 v[232:233], s[46:47], 0, v[132:133]
	s_add_i32 m0, s45, 0x2000
	s_nop 0
	global_load_lds_dwordx4 v[232:233], off
	v_lshl_add_u64 v[232:233], s[22:23], 0, v[136:137]
	s_mov_b32 m0, s33
	s_nop 0
	global_load_lds_dwordx4 v[232:233], off
	s_mov_b32 m0, s34
	s_nop 0
	global_load_lds_dwordx4 v[234:235], off
	s_waitcnt vmcnt(8)
	s_waitcnt lgkmcnt(0)
	s_barrier
; #define PG8_STAGE(bufoff, gbase, voff) do { _Pragma("unroll") for (int _i = 0; _i < 2; ++_i) \
;         __builtin_amdgcn_global_load_lds((const unsigned*)((const char*)(gbase) + (voff)[_i]), (PG8_LAS unsigned*)(lds + (bufoff) + ldsw + _i * 8192), 16, 0, 0); } while (0)
; #define PG8_LDA(dst, b, h) do { _Pragma("unroll") for (int m = 0; m < 4; ++m) _Pragma("unroll") for (int k = 0; k < 2; ++k) dst[m][k] = *(const PG8_LAS bf16x8*)(lds + PG8_SA(b, h) + aoffk[k] + m * 2048); } while (0)
; #define PG8_LDB(dst, b, h) do { _Pragma("unroll") for (int n = 0; n < 2; ++n) _Pragma("unroll") for (int k = 0; k < 2; ++k) dst[n][k] = *(const PG8_LAS bf16x8*)(lds + PG8_SB(b, h) + boffk[k] + n * 2048); } while (0)
; #define PG8_MMA(ai, bj, At, Bt) do { __builtin_amdgcn_s_setprio(1); _Pragma("unroll") for (int m = 0; m < 4; ++m) _Pragma("unroll") for (int n = 0; n < 2; ++n) _Pragma("unroll") for (int k = 0; k < 2; ++k) \
;         acc[ai][bj][m][n] = __builtin_amdgcn_mfma_f32_16x16x32_bf16(Bt[n][k], At[m][k], acc[ai][bj][m][n], 0, 0, 0); __builtin_amdgcn_s_setprio(0); } while (0)
; #define PG8_WAIT_V(n) asm volatile("s_waitcnt vmcnt(" #n ")" ::: "memory")
; #define PG8_WAIT_L(n) asm volatile("s_waitcnt lgkmcnt(" #n ")" ::: "memory")
; #define PG8_BAR __builtin_amdgcn_s_barrier()
; #define PG8_SCHED __builtin_amdgcn_sched_barrier(0)
; template <class Epi, class Sched, bool ALIGN_EPI = false, bool SP2 = false>
; __device__ __forceinline__ void gemm_phase(PG8_LAS unsigned char* lds, const Gemm g, const Sched& S, const Epi& E) {
;     ...
;             PG8_WAIT_V(8); PG8_WAIT_L(0); PG8_BAR; PG8_MMA(1, 0, At, B0); PG8_MMA(1, 1, At, B1); PG8_BAR; PG8_SCHED;
;             PG8_LDB(B0, 1, 0); PG8_LDB(B1, 1, 1); PG8_SCHED; PG8_LDA(At, 1, 0); PG8_STAGE(PG8_SA(0, 1), a2 + hstepA, voffA);
;             PG8_WAIT_V(8); PG8_WAIT_L(0); PG8_BAR; PG8_MMA(0, 0, At, B0); PG8_MMA(0, 1, At, B1); PG8_BAR; PG8_SCHED;
	v_mfma_f32_16x16x32_bf16 v[64:67], v[142:145], v[184:187], v[64:67]
	v_mfma_f32_16x16x32_bf16 v[60:63], v[156:159], v[184:187], v[60:63]
	v_mfma_f32_16x16x32_bf16 v[56:59], v[142:145], v[192:195], v[56:59]
	v_mfma_f32_16x16x32_bf16 v[48:51], v[156:159], v[192:195], v[48:51]
	v_mfma_f32_16x16x32_bf16 v[40:43], v[142:145], v[200:203], v[40:43]
	v_mfma_f32_16x16x32_bf16 v[32:35], v[156:159], v[200:203], v[32:35]
	v_mfma_f32_16x16x32_bf16 v[24:27], v[142:145], v[208:211], v[24:27]
	v_mfma_f32_16x16x32_bf16 v[16:19], v[156:159], v[208:211], v[16:19]
	v_mfma_f32_16x16x32_bf16 v[64:67], v[152:155], v[188:191], v[64:67]
	v_mfma_f32_16x16x32_bf16 v[60:63], v[160:163], v[188:191], v[60:63]
	v_mfma_f32_16x16x32_bf16 v[56:59], v[152:155], v[196:199], v[56:59]
	v_mfma_f32_16x16x32_bf16 v[48:51], v[160:163], v[196:199], v[48:51]
	v_mfma_f32_16x16x32_bf16 v[40:43], v[152:155], v[204:207], v[40:43]
	v_mfma_f32_16x16x32_bf16 v[32:35], v[160:163], v[204:207], v[32:35]
	v_mfma_f32_16x16x32_bf16 v[24:27], v[152:155], v[226:229], v[24:27]
	v_mfma_f32_16x16x32_bf16 v[16:19], v[160:163], v[226:229], v[16:19]
	v_mfma_f32_16x16x32_bf16 v[52:55], v[164:167], v[184:187], v[52:55]
	v_mfma_f32_16x16x32_bf16 v[44:47], v[176:179], v[184:187], v[44:47]
	v_mfma_f32_16x16x32_bf16 v[36:39], v[164:167], v[192:195], v[36:39]
	v_mfma_f32_16x16x32_bf16 v[28:31], v[176:179], v[192:195], v[28:31]
	v_mfma_f32_16x16x32_bf16 v[20:23], v[164:167], v[200:203], v[20:23]
	v_mfma_f32_16x16x32_bf16 v[12:15], v[176:179], v[200:203], v[12:15]
	v_mfma_f32_16x16x32_bf16 v[8:11], v[164:167], v[208:211], v[8:11]
	v_mfma_f32_16x16x32_bf16 v[4:7], v[176:179], v[208:211], v[4:7]
	v_mfma_f32_16x16x32_bf16 v[52:55], v[172:175], v[188:191], v[52:55]
	v_mfma_f32_16x16x32_bf16 v[44:47], v[180:183], v[188:191], v[44:47]
	v_mfma_f32_16x16x32_bf16 v[36:39], v[172:175], v[196:199], v[36:39]
	v_mfma_f32_16x16x32_bf16 v[28:31], v[180:183], v[196:199], v[28:31]
	v_mfma_f32_16x16x32_bf16 v[20:23], v[172:175], v[204:207], v[20:23]
	v_mfma_f32_16x16x32_bf16 v[12:15], v[180:183], v[204:207], v[12:15]
	v_mfma_f32_16x16x32_bf16 v[8:11], v[172:175], v[226:229], v[8:11]
	v_mfma_f32_16x16x32_bf16 v[4:7], v[180:183], v[226:229], v[4:7]
	s_barrier
	s_add_i32 s45, 0, 0x18000
	v_add_u32_e32 v142, s45, v147
	v_add_u32_e32 v151, s45, v148
	ds_read_b128 v[142:145], v142
	ds_read_b128 v[152:155], v151
	v_add_u32_e32 v151, s51, v147
	v_add_u32_e32 v160, s51, v148
	s_add_i32 s46, 0, 0x1c000
	ds_read_b128 v[156:159], v151
	ds_read_b128 v[160:163], v160
	v_add_u32_e32 v151, s46, v147
	v_add_u32_e32 v168, s46, v148
	ds_read_b128 v[164:167], v151
	ds_read_b128 v[172:175], v168
	v_add_u32_e32 v151, s52, v147
	v_add_u32_e32 v168, s52, v148
	ds_read_b128 v[176:179], v151
	ds_read_b128 v[180:183], v168
	s_add_u32 s22, s22, 0x80000
	s_addc_u32 s23, s23, 0
	s_mov_b32 m0, s35
	v_lshl_add_u64 v[236:237], s[22:23], 0, v[136:137]
	ds_read_b128 v[184:187], v150 offset:32768
	ds_read_b128 v[188:191], v150 offset:33792
	ds_read_b128 v[192:195], v150 offset:34816
	ds_read_b128 v[196:199], v150 offset:35840
	ds_read_b128 v[200:203], v150 offset:36864
	ds_read_b128 v[204:207], v150 offset:37888
	ds_read_b128 v[208:211], v150 offset:38912
	ds_read_b128 v[226:229], v150 offset:39936
	global_load_lds_dwordx4 v[236:237], off
	v_lshl_add_u64 v[236:237], s[22:23], 0, v[134:135]
	s_mov_b32 m0, s36
	s_nop 0
	global_load_lds_dwordx4 v[236:237], off
	s_waitcnt vmcnt(8)
	s_waitcnt lgkmcnt(0)
	s_barrier
	v_mfma_f32_16x16x32_bf16 v[128:131], v[142:145], v[184:187], v[128:131]
	v_mfma_f32_16x16x32_bf16 v[124:127], v[156:159], v[184:187], v[124:127]
	v_mfma_f32_16x16x32_bf16 v[120:123], v[142:145], v[192:195], v[120:123]
	v_mfma_f32_16x16x32_bf16 v[112:115], v[156:159], v[192:195], v[112:115]
	v_mfma_f32_16x16x32_bf16 v[104:107], v[142:145], v[200:203], v[104:107]
	v_mfma_f32_16x16x32_bf16 v[96:99], v[156:159], v[200:203], v[96:99]
	v_mfma_f32_16x16x32_bf16 v[88:91], v[142:145], v[208:211], v[88:91]
	v_mfma_f32_16x16x32_bf16 v[80:83], v[156:159], v[208:211], v[80:83]
	v_mfma_f32_16x16x32_bf16 v[128:131], v[152:155], v[188:191], v[128:131]
	v_mfma_f32_16x16x32_bf16 v[124:127], v[160:163], v[188:191], v[124:127]
	v_mfma_f32_16x16x32_bf16 v[120:123], v[152:155], v[196:199], v[120:123]
	v_mfma_f32_16x16x32_bf16 v[112:115], v[160:163], v[196:199], v[112:115]
	v_mfma_f32_16x16x32_bf16 v[104:107], v[152:155], v[204:207], v[104:107]
	v_mfma_f32_16x16x32_bf16 v[96:99], v[160:163], v[204:207], v[96:99]
	v_mfma_f32_16x16x32_bf16 v[88:91], v[152:155], v[226:229], v[88:91]
	v_mfma_f32_16x16x32_bf16 v[80:83], v[160:163], v[226:229], v[80:83]
	v_mfma_f32_16x16x32_bf16 v[116:119], v[164:167], v[184:187], v[116:119]
	v_mfma_f32_16x16x32_bf16 v[108:111], v[176:179], v[184:187], v[108:111]
	v_mfma_f32_16x16x32_bf16 v[100:103], v[164:167], v[192:195], v[100:103]
	v_mfma_f32_16x16x32_bf16 v[92:95], v[176:179], v[192:195], v[92:95]
	v_mfma_f32_16x16x32_bf16 v[84:87], v[164:167], v[200:203], v[84:87]
	v_mfma_f32_16x16x32_bf16 v[76:79], v[176:179], v[200:203], v[76:79]
	v_mfma_f32_16x16x32_bf16 v[72:75], v[164:167], v[208:211], v[72:75]
	v_mfma_f32_16x16x32_bf16 v[68:71], v[176:179], v[208:211], v[68:71]
	v_mfma_f32_16x16x32_bf16 v[116:119], v[172:175], v[188:191], v[116:119]
	v_mfma_f32_16x16x32_bf16 v[108:111], v[180:183], v[188:191], v[108:111]
	v_mfma_f32_16x16x32_bf16 v[100:103], v[172:175], v[196:199], v[100:103]
	v_mfma_f32_16x16x32_bf16 v[92:95], v[180:183], v[196:199], v[92:95]
	v_mfma_f32_16x16x32_bf16 v[84:87], v[172:175], v[204:207], v[84:87]
	v_mfma_f32_16x16x32_bf16 v[76:79], v[180:183], v[204:207], v[76:79]
	v_mfma_f32_16x16x32_bf16 v[72:75], v[172:175], v[226:229], v[72:75]
	v_mfma_f32_16x16x32_bf16 v[68:71], v[180:183], v[226:229], v[68:71]
	s_barrier
; #define PG8_STAGE(bufoff, gbase, voff) do { _Pragma("unroll") for (int _i = 0; _i < 2; ++_i) \
;         __builtin_amdgcn_global_load_lds((const unsigned*)((const char*)(gbase) + (voff)[_i]), (PG8_LAS unsigned*)(lds + (bufoff) + ldsw + _i * 8192), 16, 0, 0); } while (0)
; #define PG8_LDA(dst, b, h) do { _Pragma("unroll") for (int m = 0; m < 4; ++m) _Pragma("unroll") for (int k = 0; k < 2; ++k) dst[m][k] = *(const PG8_LAS bf16x8*)(lds + PG8_SA(b, h) + aoffk[k] + m * 2048); } while (0)
; #define PG8_MMA(ai, bj, At, Bt) do { __builtin_amdgcn_s_setprio(1); _Pragma("unroll") for (int m = 0; m < 4; ++m) _Pragma("unroll") for (int n = 0; n < 2; ++n) _Pragma("unroll") for (int k = 0; k < 2; ++k) \
;         acc[ai][bj][m][n] = __builtin_amdgcn_mfma_f32_16x16x32_bf16(Bt[n][k], At[m][k], acc[ai][bj][m][n], 0, 0, 0); __builtin_amdgcn_s_setprio(0); } while (0)
; #define PG8_WAIT_V(n) asm volatile("s_waitcnt vmcnt(" #n ")" ::: "memory")
; #define PG8_WAIT_L(n) asm volatile("s_waitcnt lgkmcnt(" #n ")" ::: "memory")
; #define PG8_BAR __builtin_amdgcn_s_barrier()
; #define PG8_SCHED __builtin_amdgcn_sched_barrier(0)
; template <class Epi, class Sched, bool ALIGN_EPI = false, bool SP2 = false>
; __device__ __forceinline__ void gemm_phase(PG8_LAS unsigned char* lds, const Gemm g, const Sched& S, const Epi& E) {
;     ...
;             PG8_LDA(At, 1, 1); PG8_STAGE(PG8_SB(1, 0), b3, voffB); PG8_STAGE(PG8_SB(1, 1), b3 + hstepB, voffB); PG8_STAGE(PG8_SA(1, 0), a3, voffA);
;             PG8_WAIT_V(8); PG8_WAIT_L(0); PG8_BAR; PG8_MMA(1, 0, At, B0); PG8_MMA(1, 1, At, B1); PG8_BAR; PG8_SCHED;
	s_add_i32 s22, s45, s30
	v_lshl_add_u64 v[212:213], v[212:213], 0, s[56:57]
	s_mov_b32 m0, s22
	ds_read_b128 v[184:187], v150 offset:49152
	ds_read_b128 v[188:191], v150 offset:50176
	ds_read_b128 v[192:195], v150 offset:51200
	ds_read_b128 v[196:199], v150 offset:52224
	ds_read_b128 v[200:203], v150 offset:53248
	ds_read_b128 v[204:207], v150 offset:54272
	ds_read_b128 v[208:211], v150 offset:55296
	ds_read_b128 v[226:229], v150 offset:56320
	global_load_lds_dwordx4 v[212:213], off
	s_add_i32 m0, s22, 0x2000
	s_add_u32 s20, s20, 0x80080
	v_lshl_add_u64 v[212:213], v[230:231], 0, s[56:57]
	s_addc_u32 s21, s21, 0
	s_add_i32 s22, s46, s30
	global_load_lds_dwordx4 v[212:213], off
	v_lshl_add_u64 v[212:213], s[20:21], 0, v[2:3]
	s_mov_b32 m0, s22
	s_nop 0
	global_load_lds_dwordx4 v[212:213], off
	v_lshl_add_u64 v[212:213], s[20:21], 0, v[132:133]
	s_add_i32 m0, s22, 0x2000
	s_nop 0
	global_load_lds_dwordx4 v[212:213], off
	v_lshl_add_u64 v[212:213], v[232:233], 0, s[56:57]
	s_mov_b32 m0, s37
	s_nop 0
	global_load_lds_dwordx4 v[212:213], off
	v_lshl_add_u64 v[212:213], v[234:235], 0, s[56:57]
	s_mov_b32 m0, s38
	s_nop 0
	global_load_lds_dwordx4 v[212:213], off
	s_waitcnt vmcnt(8)
	s_waitcnt lgkmcnt(0)
	s_barrier
	v_mfma_f32_16x16x32_bf16 v[64:67], v[142:145], v[184:187], v[64:67]
	v_mfma_f32_16x16x32_bf16 v[60:63], v[156:159], v[184:187], v[60:63]
	v_mfma_f32_16x16x32_bf16 v[56:59], v[142:145], v[192:195], v[56:59]
	v_mfma_f32_16x16x32_bf16 v[48:51], v[156:159], v[192:195], v[48:51]
	v_mfma_f32_16x16x32_bf16 v[40:43], v[142:145], v[200:203], v[40:43]
	v_mfma_f32_16x16x32_bf16 v[32:35], v[156:159], v[200:203], v[32:35]
	v_mfma_f32_16x16x32_bf16 v[24:27], v[142:145], v[208:211], v[24:27]
	v_mfma_f32_16x16x32_bf16 v[16:19], v[156:159], v[208:211], v[16:19]
	v_mfma_f32_16x16x32_bf16 v[64:67], v[152:155], v[188:191], v[64:67]
	v_mfma_f32_16x16x32_bf16 v[60:63], v[160:163], v[188:191], v[60:63]
	v_mfma_f32_16x16x32_bf16 v[56:59], v[152:155], v[196:199], v[56:59]
	v_mfma_f32_16x16x32_bf16 v[48:51], v[160:163], v[196:199], v[48:51]
	v_mfma_f32_16x16x32_bf16 v[40:43], v[152:155], v[204:207], v[40:43]
	v_mfma_f32_16x16x32_bf16 v[32:35], v[160:163], v[204:207], v[32:35]
	v_mfma_f32_16x16x32_bf16 v[24:27], v[152:155], v[226:229], v[24:27]
	v_mfma_f32_16x16x32_bf16 v[16:19], v[160:163], v[226:229], v[16:19]
	v_mfma_f32_16x16x32_bf16 v[52:55], v[164:167], v[184:187], v[52:55]
	v_mfma_f32_16x16x32_bf16 v[44:47], v[176:179], v[184:187], v[44:47]
	v_mfma_f32_16x16x32_bf16 v[36:39], v[164:167], v[192:195], v[36:39]
	v_mfma_f32_16x16x32_bf16 v[28:31], v[176:179], v[192:195], v[28:31]
	v_mfma_f32_16x16x32_bf16 v[20:23], v[164:167], v[200:203], v[20:23]
	v_mfma_f32_16x16x32_bf16 v[12:15], v[176:179], v[200:203], v[12:15]
	v_mfma_f32_16x16x32_bf16 v[8:11], v[164:167], v[208:211], v[8:11]
	v_mfma_f32_16x16x32_bf16 v[4:7], v[176:179], v[208:211], v[4:7]
	v_mfma_f32_16x16x32_bf16 v[52:55], v[172:175], v[188:191], v[52:55]
	v_mfma_f32_16x16x32_bf16 v[44:47], v[180:183], v[188:191], v[44:47]
	v_mfma_f32_16x16x32_bf16 v[36:39], v[172:175], v[196:199], v[36:39]
	v_mfma_f32_16x16x32_bf16 v[28:31], v[180:183], v[196:199], v[28:31]
	v_mfma_f32_16x16x32_bf16 v[20:23], v[172:175], v[204:207], v[20:23]
	v_mfma_f32_16x16x32_bf16 v[12:15], v[180:183], v[204:207], v[12:15]
	v_mfma_f32_16x16x32_bf16 v[8:11], v[172:175], v[226:229], v[8:11]
	v_mfma_f32_16x16x32_bf16 v[4:7], v[180:183], v[226:229], v[4:7]
	s_barrier
	s_add_i32 s44, s44, 2
	s_add_u32 s18, s18, 0x100
	s_addc_u32 s19, s19, 0
	s_add_u32 s42, s42, 0x100
	s_addc_u32 s43, s43, 0
	s_cmp_gt_u32 s44, 29
	s_cbranch_scc0 .LBB0_663
	s_and_b64 vcc, exec, s[4:5]
	s_cbranch_vccz .LBB0_666
	s_barrier

; #define PG8_STAGE(bufoff, gbase, voff) do { _Pragma("unroll") for (int _i = 0; _i < 2; ++_i) \
;         __builtin_amdgcn_global_load_lds((const unsigned*)((const char*)(gbase) + (voff)[_i]), (PG8_LAS unsigned*)(lds + (bufoff) + ldsw + _i * 8192), 16, 0, 0); } while (0)
; #define PG8_LDA(dst, b, h) do { _Pragma("unroll") for (int m = 0; m < 4; ++m) _Pragma("unroll") for (int k = 0; k < 2; ++k) dst[m][k] = *(const PG8_LAS bf16x8*)(lds + PG8_SA(b, h) + aoffk[k] + m * 2048); } while (0)
; #define PG8_LDB(dst, b, h) do { _Pragma("unroll") for (int n = 0; n < 2; ++n) _Pragma("unroll") for (int k = 0; k < 2; ++k) dst[n][k] = *(const PG8_LAS bf16x8*)(lds + PG8_SB(b, h) + boffk[k] + n * 2048); } while (0)
; #define PG8_MMA(ai, bj, At, Bt) do { __builtin_amdgcn_s_setprio(1); _Pragma("unroll") for (int m = 0; m < 4; ++m) _Pragma("unroll") for (int n = 0; n < 2; ++n) _Pragma("unroll") for (int k = 0; k < 2; ++k) \
;         acc[ai][bj][m][n] = __builtin_amdgcn_mfma_f32_16x16x32_bf16(Bt[n][k], At[m][k], acc[ai][bj][m][n], 0, 0, 0); __builtin_amdgcn_s_setprio(0); } while (0)
; #define PG8_WAIT_V(n) asm volatile("s_waitcnt vmcnt(" #n ")" ::: "memory")
; #define PG8_WAIT_L(n) asm volatile("s_waitcnt lgkmcnt(" #n ")" ::: "memory")
; #define PG8_BAR __builtin_amdgcn_s_barrier()
; template <class Epi, class Sched, bool ALIGN_EPI = false, bool SP2 = false>
; __device__ __forceinline__ void gemm_phase(PG8_LAS unsigned char* lds, const Gemm g, const Sched& S, const Epi& E) {
;     ...
;             const bool last = (t == nt - 2);
;             const char* a1 = cA + (size_t)(t + 1) * kstep;
;             const char* a2 = last ? nA : cA + (size_t)(t + 2) * kstep; const char* b2 = last ? nB : cB + (size_t)(t + 2) * kstep;
;             const char* a3 = a2 + kstep; const char* b3 = b2 + kstep;
;             if (last && has_next) S.a_ready(nxt);
;             if constexpr (SP2) {
;             PG8_LDB(B0, 0, 0); PG8_LDB(B1, 0, 1); PG8_SCHED; PG8_LDA(At, 0, 0); PG8_STAGE(PG8_SA(1, 1), a1 + hstepA, voffA);
;             PG8_WAIT_V(8); PG8_WAIT_L(0); PG8_BAR; PG8_MMA(0, 0, At, B0); PG8_MMA(0, 1, At, B1); PG8_BAR; PG8_SCHED;
;             PG8_LDA(At, 0, 1); PG8_STAGE(PG8_SB(0, 0), b2, voffB); PG8_STAGE(PG8_SB(0, 1), b2 + hstepB, voffB); PG8_STAGE(PG8_SA(0, 0), a2, voffA);
;             PG8_WAIT_V(8); PG8_WAIT_L(0); PG8_BAR; PG8_MMA(1, 0, At, B0); PG8_MMA(1, 1, At, B1); PG8_BAR; PG8_SCHED;
.LBB0_1293:
	s_add_i32 s48, s22, 2
	s_add_u32 s23, s20, 0xfff80080
	s_addc_u32 s24, s21, -1
	s_add_i32 s49, 0, 0x10000
	s_cmp_eq_u32 s11, s22
	v_add_u32_e32 v142, s49, v145
	s_cselect_b32 s25, s17, s24
	s_cselect_b32 s24, s16, s23
	v_add_u32_e32 v143, s49, v146
	ds_read_b128 v[150:153], v142
	ds_read_b128 v[154:157], v143
	v_add_u32_e32 v142, s53, v145
	s_cselect_b32 s23, s19, s15
	s_cselect_b32 s22, s18, s13
	s_add_i32 s52, 0, 0x14000
	v_add_u32_e32 v143, s53, v146
	ds_read_b128 v[158:161], v142
	ds_read_b128 v[162:165], v143
	v_add_u32_e32 v142, s52, v145
	v_add_u32_e32 v143, s52, v146
	ds_read_b128 v[172:175], v142
	ds_read_b128 v[176:179], v143
	v_add_u32_e32 v142, s54, v145
	v_add_u32_e32 v143, s54, v146
	ds_read_b128 v[180:183], v142
	ds_read_b128 v[184:187], v143
	v_lshl_add_u64 v[142:143], s[20:21], 0, v[138:139]
	s_add_i32 m0, s5, 0xc000
	ds_read_b128 v[188:191], v148
	ds_read_b128 v[192:195], v148 offset:1024
	ds_read_b128 v[196:199], v148 offset:2048
	ds_read_b128 v[200:203], v148 offset:3072
	ds_read_b128 v[204:207], v148 offset:4096
	ds_read_b128 v[208:211], v148 offset:5120
	ds_read_b128 v[226:229], v148 offset:6144
	ds_read_b128 v[230:233], v148 offset:7168
	global_load_lds_dwordx4 v[142:143], off
	v_lshl_add_u64 v[142:143], s[20:21], 0, v[140:141]
	s_add_i32 m0, s5, 0xe000
	s_nop 0
	global_load_lds_dwordx4 v[142:143], off
	s_waitcnt vmcnt(8)
	s_waitcnt lgkmcnt(0)
	s_barrier
	v_mfma_f32_16x16x32_bf16 v[128:131], v[150:153], v[188:191], v[128:131]
	v_mfma_f32_16x16x32_bf16 v[124:127], v[158:161], v[188:191], v[124:127]
	v_mfma_f32_16x16x32_bf16 v[120:123], v[150:153], v[196:199], v[120:123]
	v_mfma_f32_16x16x32_bf16 v[112:115], v[158:161], v[196:199], v[112:115]
	v_mfma_f32_16x16x32_bf16 v[104:107], v[150:153], v[204:207], v[104:107]
	v_mfma_f32_16x16x32_bf16 v[96:99], v[158:161], v[204:207], v[96:99]
	v_mfma_f32_16x16x32_bf16 v[88:91], v[150:153], v[226:229], v[88:91]
	v_mfma_f32_16x16x32_bf16 v[80:83], v[158:161], v[226:229], v[80:83]
	v_mfma_f32_16x16x32_bf16 v[128:131], v[154:157], v[192:195], v[128:131]
	v_mfma_f32_16x16x32_bf16 v[124:127], v[162:165], v[192:195], v[124:127]
	v_mfma_f32_16x16x32_bf16 v[120:123], v[154:157], v[200:203], v[120:123]
	v_mfma_f32_16x16x32_bf16 v[112:115], v[162:165], v[200:203], v[112:115]
	v_mfma_f32_16x16x32_bf16 v[104:107], v[154:157], v[208:211], v[104:107]
	v_mfma_f32_16x16x32_bf16 v[96:99], v[162:165], v[208:211], v[96:99]
	v_mfma_f32_16x16x32_bf16 v[88:91], v[154:157], v[230:233], v[88:91]
	v_mfma_f32_16x16x32_bf16 v[80:83], v[162:165], v[230:233], v[80:83]
	v_mfma_f32_16x16x32_bf16 v[116:119], v[172:175], v[188:191], v[116:119]
	v_mfma_f32_16x16x32_bf16 v[108:111], v[180:183], v[188:191], v[108:111]
	v_mfma_f32_16x16x32_bf16 v[100:103], v[172:175], v[196:199], v[100:103]
	v_mfma_f32_16x16x32_bf16 v[92:95], v[180:183], v[196:199], v[92:95]
	v_mfma_f32_16x16x32_bf16 v[84:87], v[172:175], v[204:207], v[84:87]
	v_mfma_f32_16x16x32_bf16 v[76:79], v[180:183], v[204:207], v[76:79]
	v_mfma_f32_16x16x32_bf16 v[72:75], v[172:175], v[226:229], v[72:75]
	v_mfma_f32_16x16x32_bf16 v[68:71], v[180:183], v[226:229], v[68:71]
	v_mfma_f32_16x16x32_bf16 v[116:119], v[176:179], v[192:195], v[116:119]
	v_mfma_f32_16x16x32_bf16 v[108:111], v[184:187], v[192:195], v[108:111]
	v_mfma_f32_16x16x32_bf16 v[100:103], v[176:179], v[200:203], v[100:103]
	v_mfma_f32_16x16x32_bf16 v[92:95], v[184:187], v[200:203], v[92:95]
	v_mfma_f32_16x16x32_bf16 v[84:87], v[176:179], v[208:211], v[84:87]
	v_mfma_f32_16x16x32_bf16 v[76:79], v[184:187], v[208:211], v[76:79]
	v_mfma_f32_16x16x32_bf16 v[72:75], v[176:179], v[230:233], v[72:75]
	v_mfma_f32_16x16x32_bf16 v[68:71], v[184:187], v[230:233], v[68:71]
	s_barrier
	s_add_i32 s49, s49, s33
	v_lshl_add_u64 v[142:143], s[22:23], 0, v[2:3]
	s_mov_b32 m0, s49
	ds_read_b128 v[188:191], v148 offset:16384
	ds_read_b128 v[192:195], v148 offset:17408
	ds_read_b128 v[196:199], v148 offset:18432
	ds_read_b128 v[200:203], v148 offset:19456
	ds_read_b128 v[204:207], v148 offset:20480
	ds_read_b128 v[208:211], v148 offset:21504
	ds_read_b128 v[226:229], v148 offset:22528
	ds_read_b128 v[230:233], v148 offset:23552
	global_load_lds_dwordx4 v[142:143], off
	s_add_i32 m0, s49, 0x2000
	s_add_u32 s50, s22, 0x80000
	v_lshl_add_u64 v[166:167], s[22:23], 0, v[136:137]
	s_addc_u32 s51, s23, 0
	s_add_i32 s49, s52, s33
	global_load_lds_dwordx4 v[166:167], off
	v_lshl_add_u64 v[212:213], s[50:51], 0, v[2:3]
	s_mov_b32 m0, s49
	v_lshl_add_u64 v[220:221], s[24:25], 0, v[134:135]
	global_load_lds_dwordx4 v[212:213], off
	v_lshl_add_u64 v[212:213], s[50:51], 0, v[136:137]
	s_add_i32 m0, s49, 0x2000
	s_nop 0
	global_load_lds_dwordx4 v[212:213], off
	v_lshl_add_u64 v[212:213], s[24:25], 0, v[132:133]
	s_mov_b32 m0, s5
	s_nop 0
	global_load_lds_dwordx4 v[212:213], off
	s_mov_b32 m0, s7
	s_nop 0
	global_load_lds_dwordx4 v[220:221], off
	s_waitcnt vmcnt(8)
	s_waitcnt lgkmcnt(0)
	s_barrier
; #define PG8_STAGE(bufoff, gbase, voff) do { _Pragma("unroll") for (int _i = 0; _i < 2; ++_i) \
;         __builtin_amdgcn_global_load_lds((const unsigned*)((const char*)(gbase) + (voff)[_i]), (PG8_LAS unsigned*)(lds + (bufoff) + ldsw + _i * 8192), 16, 0, 0); } while (0)
; #define PG8_LDA(dst, b, h) do { _Pragma("unroll") for (int m = 0; m < 4; ++m) _Pragma("unroll") for (int k = 0; k < 2; ++k) dst[m][k] = *(const PG8_LAS bf16x8*)(lds + PG8_SA(b, h) + aoffk[k] + m * 2048); } while (0)
; #define PG8_LDB(dst, b, h) do { _Pragma("unroll") for (int n = 0; n < 2; ++n) _Pragma("unroll") for (int k = 0; k < 2; ++k) dst[n][k] = *(const PG8_LAS bf16x8*)(lds + PG8_SB(b, h) + boffk[k] + n * 2048); } while (0)
; #define PG8_MMA(ai, bj, At, Bt) do { __builtin_amdgcn_s_setprio(1); _Pragma("unroll") for (int m = 0; m < 4; ++m) _Pragma("unroll") for (int n = 0; n < 2; ++n) _Pragma("unroll") for (int k = 0; k < 2; ++k) \
;         acc[ai][bj][m][n] = __builtin_amdgcn_mfma_f32_16x16x32_bf16(Bt[n][k], At[m][k], acc[ai][bj][m][n], 0, 0, 0); __builtin_amdgcn_s_setprio(0); } while (0)
; #define PG8_WAIT_V(n) asm volatile("s_waitcnt vmcnt(" #n ")" ::: "memory")
; #define PG8_WAIT_L(n) asm volatile("s_waitcnt lgkmcnt(" #n ")" ::: "memory")
; #define PG8_BAR __builtin_amdgcn_s_barrier()
; #define PG8_SCHED __builtin_amdgcn_sched_barrier(0)
; template <class Epi, class Sched, bool ALIGN_EPI = false, bool SP2 = false>
; __device__ __forceinline__ void gemm_phase(PG8_LAS unsigned char* lds, const Gemm g, const Sched& S, const Epi& E) {
;     ...
;             PG8_WAIT_V(8); PG8_WAIT_L(0); PG8_BAR; PG8_MMA(1, 0, At, B0); PG8_MMA(1, 1, At, B1); PG8_BAR; PG8_SCHED;
;             PG8_LDB(B0, 1, 0); PG8_LDB(B1, 1, 1); PG8_SCHED; PG8_LDA(At, 1, 0); PG8_STAGE(PG8_SA(0, 1), a2 + hstepA, voffA);
;             PG8_WAIT_V(8); PG8_WAIT_L(0); PG8_BAR; PG8_MMA(0, 0, At, B0); PG8_MMA(0, 1, At, B1); PG8_BAR; PG8_SCHED;
	v_mfma_f32_16x16x32_bf16 v[64:67], v[150:153], v[188:191], v[64:67]
	v_mfma_f32_16x16x32_bf16 v[60:63], v[158:161], v[188:191], v[60:63]
	v_mfma_f32_16x16x32_bf16 v[56:59], v[150:153], v[196:199], v[56:59]
	v_mfma_f32_16x16x32_bf16 v[48:51], v[158:161], v[196:199], v[48:51]
	v_mfma_f32_16x16x32_bf16 v[40:43], v[150:153], v[204:207], v[40:43]
	v_mfma_f32_16x16x32_bf16 v[32:35], v[158:161], v[204:207], v[32:35]
	v_mfma_f32_16x16x32_bf16 v[24:27], v[150:153], v[226:229], v[24:27]
	v_mfma_f32_16x16x32_bf16 v[16:19], v[158:161], v[226:229], v[16:19]
	v_mfma_f32_16x16x32_bf16 v[64:67], v[154:157], v[192:195], v[64:67]
	v_mfma_f32_16x16x32_bf16 v[60:63], v[162:165], v[192:195], v[60:63]
	v_mfma_f32_16x16x32_bf16 v[56:59], v[154:157], v[200:203], v[56:59]
	v_mfma_f32_16x16x32_bf16 v[48:51], v[162:165], v[200:203], v[48:51]
	v_mfma_f32_16x16x32_bf16 v[40:43], v[154:157], v[208:211], v[40:43]
	v_mfma_f32_16x16x32_bf16 v[32:35], v[162:165], v[208:211], v[32:35]
	v_mfma_f32_16x16x32_bf16 v[24:27], v[154:157], v[230:233], v[24:27]
	v_mfma_f32_16x16x32_bf16 v[16:19], v[162:165], v[230:233], v[16:19]
	v_mfma_f32_16x16x32_bf16 v[52:55], v[172:175], v[188:191], v[52:55]
	v_mfma_f32_16x16x32_bf16 v[44:47], v[180:183], v[188:191], v[44:47]
	v_mfma_f32_16x16x32_bf16 v[36:39], v[172:175], v[196:199], v[36:39]
	v_mfma_f32_16x16x32_bf16 v[28:31], v[180:183], v[196:199], v[28:31]
	v_mfma_f32_16x16x32_bf16 v[20:23], v[172:175], v[204:207], v[20:23]
	v_mfma_f32_16x16x32_bf16 v[12:15], v[180:183], v[204:207], v[12:15]
	v_mfma_f32_16x16x32_bf16 v[8:11], v[172:175], v[226:229], v[8:11]
	v_mfma_f32_16x16x32_bf16 v[4:7], v[180:183], v[226:229], v[4:7]
	v_mfma_f32_16x16x32_bf16 v[52:55], v[176:179], v[192:195], v[52:55]
	v_mfma_f32_16x16x32_bf16 v[44:47], v[184:187], v[192:195], v[44:47]
	v_mfma_f32_16x16x32_bf16 v[36:39], v[176:179], v[200:203], v[36:39]
	v_mfma_f32_16x16x32_bf16 v[28:31], v[184:187], v[200:203], v[28:31]
	v_mfma_f32_16x16x32_bf16 v[20:23], v[176:179], v[208:211], v[20:23]
	v_mfma_f32_16x16x32_bf16 v[12:15], v[184:187], v[208:211], v[12:15]
	v_mfma_f32_16x16x32_bf16 v[8:11], v[176:179], v[230:233], v[8:11]
	v_mfma_f32_16x16x32_bf16 v[4:7], v[184:187], v[230:233], v[4:7]
	s_barrier
	s_add_i32 s49, 0, 0x18000
	v_add_u32_e32 v149, s49, v145
	v_add_u32_e32 v154, s49, v146
	ds_read_b128 v[150:153], v149
	ds_read_b128 v[154:157], v154
	v_add_u32_e32 v149, s55, v145
	v_add_u32_e32 v162, s55, v146
	s_add_i32 s50, 0, 0x1c000
	ds_read_b128 v[158:161], v149
	ds_read_b128 v[162:165], v162
	v_add_u32_e32 v149, s50, v145
	v_add_u32_e32 v168, s50, v146
	ds_read_b128 v[172:175], v149
	ds_read_b128 v[176:179], v168
	v_add_u32_e32 v149, s56, v145
	v_add_u32_e32 v168, s56, v146
	ds_read_b128 v[180:183], v149
	ds_read_b128 v[184:187], v168
	s_add_u32 s24, s24, 0x80000
	s_addc_u32 s25, s25, 0
	s_mov_b32 m0, s34
	v_lshl_add_u64 v[234:235], s[24:25], 0, v[132:133]
	ds_read_b128 v[188:191], v148 offset:32768
	ds_read_b128 v[192:195], v148 offset:33792
	ds_read_b128 v[196:199], v148 offset:34816
	ds_read_b128 v[200:203], v148 offset:35840
	ds_read_b128 v[204:207], v148 offset:36864
	ds_read_b128 v[208:211], v148 offset:37888
	ds_read_b128 v[226:229], v148 offset:38912
	ds_read_b128 v[230:233], v148 offset:39936
	global_load_lds_dwordx4 v[234:235], off
	v_lshl_add_u64 v[234:235], s[24:25], 0, v[134:135]
	s_mov_b32 m0, s35
	s_nop 0
	global_load_lds_dwordx4 v[234:235], off
	s_waitcnt vmcnt(8)
	s_waitcnt lgkmcnt(0)
	s_barrier
	v_mfma_f32_16x16x32_bf16 v[128:131], v[150:153], v[188:191], v[128:131]
	v_mfma_f32_16x16x32_bf16 v[124:127], v[158:161], v[188:191], v[124:127]
	v_mfma_f32_16x16x32_bf16 v[120:123], v[150:153], v[196:199], v[120:123]
	v_mfma_f32_16x16x32_bf16 v[112:115], v[158:161], v[196:199], v[112:115]
	v_mfma_f32_16x16x32_bf16 v[104:107], v[150:153], v[204:207], v[104:107]
	v_mfma_f32_16x16x32_bf16 v[96:99], v[158:161], v[204:207], v[96:99]
	v_mfma_f32_16x16x32_bf16 v[88:91], v[150:153], v[226:229], v[88:91]
	v_mfma_f32_16x16x32_bf16 v[80:83], v[158:161], v[226:229], v[80:83]
	v_mfma_f32_16x16x32_bf16 v[128:131], v[154:157], v[192:195], v[128:131]
	v_mfma_f32_16x16x32_bf16 v[124:127], v[162:165], v[192:195], v[124:127]
	v_mfma_f32_16x16x32_bf16 v[120:123], v[154:157], v[200:203], v[120:123]
	v_mfma_f32_16x16x32_bf16 v[112:115], v[162:165], v[200:203], v[112:115]
	v_mfma_f32_16x16x32_bf16 v[104:107], v[154:157], v[208:211], v[104:107]
	v_mfma_f32_16x16x32_bf16 v[96:99], v[162:165], v[208:211], v[96:99]
	v_mfma_f32_16x16x32_bf16 v[88:91], v[154:157], v[230:233], v[88:91]
	v_mfma_f32_16x16x32_bf16 v[80:83], v[162:165], v[230:233], v[80:83]
	v_mfma_f32_16x16x32_bf16 v[116:119], v[172:175], v[188:191], v[116:119]
	v_mfma_f32_16x16x32_bf16 v[108:111], v[180:183], v[188:191], v[108:111]
	v_mfma_f32_16x16x32_bf16 v[100:103], v[172:175], v[196:199], v[100:103]
	v_mfma_f32_16x16x32_bf16 v[92:95], v[180:183], v[196:199], v[92:95]
	v_mfma_f32_16x16x32_bf16 v[84:87], v[172:175], v[204:207], v[84:87]
	v_mfma_f32_16x16x32_bf16 v[76:79], v[180:183], v[204:207], v[76:79]
	v_mfma_f32_16x16x32_bf16 v[72:75], v[172:175], v[226:229], v[72:75]
	v_mfma_f32_16x16x32_bf16 v[68:71], v[180:183], v[226:229], v[68:71]
	v_mfma_f32_16x16x32_bf16 v[116:119], v[176:179], v[192:195], v[116:119]
	v_mfma_f32_16x16x32_bf16 v[108:111], v[184:187], v[192:195], v[108:111]
	v_mfma_f32_16x16x32_bf16 v[100:103], v[176:179], v[200:203], v[100:103]
	v_mfma_f32_16x16x32_bf16 v[92:95], v[184:187], v[200:203], v[92:95]
	v_mfma_f32_16x16x32_bf16 v[84:87], v[176:179], v[208:211], v[84:87]
	v_mfma_f32_16x16x32_bf16 v[76:79], v[184:187], v[208:211], v[76:79]
	v_mfma_f32_16x16x32_bf16 v[72:75], v[176:179], v[230:233], v[72:75]
	v_mfma_f32_16x16x32_bf16 v[68:71], v[184:187], v[230:233], v[68:71]
	s_barrier
; #define PG8_STAGE(bufoff, gbase, voff) do { _Pragma("unroll") for (int _i = 0; _i < 2; ++_i) \
;         __builtin_amdgcn_global_load_lds((const unsigned*)((const char*)(gbase) + (voff)[_i]), (PG8_LAS unsigned*)(lds + (bufoff) + ldsw + _i * 8192), 16, 0, 0); } while (0)
; #define PG8_LDA(dst, b, h) do { _Pragma("unroll") for (int m = 0; m < 4; ++m) _Pragma("unroll") for (int k = 0; k < 2; ++k) dst[m][k] = *(const PG8_LAS bf16x8*)(lds + PG8_SA(b, h) + aoffk[k] + m * 2048); } while (0)
; #define PG8_MMA(ai, bj, At, Bt) do { __builtin_amdgcn_s_setprio(1); _Pragma("unroll") for (int m = 0; m < 4; ++m) _Pragma("unroll") for (int n = 0; n < 2; ++n) _Pragma("unroll") for (int k = 0; k < 2; ++k) \
;         acc[ai][bj][m][n] = __builtin_amdgcn_mfma_f32_16x16x32_bf16(Bt[n][k], At[m][k], acc[ai][bj][m][n], 0, 0, 0); __builtin_amdgcn_s_setprio(0); } while (0)
; #define PG8_WAIT_V(n) asm volatile("s_waitcnt vmcnt(" #n ")" ::: "memory")
; #define PG8_WAIT_L(n) asm volatile("s_waitcnt lgkmcnt(" #n ")" ::: "memory")
; #define PG8_BAR __builtin_amdgcn_s_barrier()
; #define PG8_SCHED __builtin_amdgcn_sched_barrier(0)
; template <class Epi, class Sched, bool ALIGN_EPI = false, bool SP2 = false>
; __device__ __forceinline__ void gemm_phase(PG8_LAS unsigned char* lds, const Gemm g, const Sched& S, const Epi& E) {
;     ...
;             PG8_LDA(At, 1, 1); PG8_STAGE(PG8_SB(1, 0), b3, voffB); PG8_STAGE(PG8_SB(1, 1), b3 + hstepB, voffB); PG8_STAGE(PG8_SA(1, 0), a3, voffA);
;             PG8_WAIT_V(8); PG8_WAIT_L(0); PG8_BAR; PG8_MMA(1, 0, At, B0); PG8_MMA(1, 1, At, B1); PG8_BAR; PG8_SCHED;
	s_add_i32 s24, s49, s33
	v_lshl_add_u64 v[142:143], v[142:143], 0, s[58:59]
	s_mov_b32 m0, s24
	ds_read_b128 v[188:191], v148 offset:49152
	ds_read_b128 v[192:195], v148 offset:50176
	ds_read_b128 v[196:199], v148 offset:51200
	ds_read_b128 v[200:203], v148 offset:52224
	ds_read_b128 v[204:207], v148 offset:53248
	ds_read_b128 v[208:211], v148 offset:54272
	ds_read_b128 v[226:229], v148 offset:55296
	ds_read_b128 v[230:233], v148 offset:56320
	global_load_lds_dwordx4 v[142:143], off
	s_add_i32 m0, s24, 0x2000
	s_add_u32 s22, s22, 0x80080
	v_lshl_add_u64 v[142:143], v[166:167], 0, s[58:59]
	s_addc_u32 s23, s23, 0
	s_add_i32 s24, s50, s33
	global_load_lds_dwordx4 v[142:143], off
	v_lshl_add_u64 v[142:143], s[22:23], 0, v[2:3]
	s_mov_b32 m0, s24
	s_nop 0
	global_load_lds_dwordx4 v[142:143], off
	v_lshl_add_u64 v[142:143], s[22:23], 0, v[136:137]
	s_add_i32 m0, s24, 0x2000
	s_nop 0
	global_load_lds_dwordx4 v[142:143], off
	v_lshl_add_u64 v[142:143], v[212:213], 0, s[58:59]
	s_mov_b32 m0, s40
	s_nop 0
	global_load_lds_dwordx4 v[142:143], off
	v_lshl_add_u64 v[142:143], v[220:221], 0, s[58:59]
	s_mov_b32 m0, s41
	s_nop 0
	global_load_lds_dwordx4 v[142:143], off
	s_waitcnt vmcnt(8)
	s_waitcnt lgkmcnt(0)
	s_barrier
	v_mfma_f32_16x16x32_bf16 v[64:67], v[150:153], v[188:191], v[64:67]
	v_mfma_f32_16x16x32_bf16 v[60:63], v[158:161], v[188:191], v[60:63]
	v_mfma_f32_16x16x32_bf16 v[56:59], v[150:153], v[196:199], v[56:59]
	v_mfma_f32_16x16x32_bf16 v[48:51], v[158:161], v[196:199], v[48:51]
	v_mfma_f32_16x16x32_bf16 v[40:43], v[150:153], v[204:207], v[40:43]
	v_mfma_f32_16x16x32_bf16 v[32:35], v[158:161], v[204:207], v[32:35]
	v_mfma_f32_16x16x32_bf16 v[24:27], v[150:153], v[226:229], v[24:27]
	v_mfma_f32_16x16x32_bf16 v[16:19], v[158:161], v[226:229], v[16:19]
	v_mfma_f32_16x16x32_bf16 v[64:67], v[154:157], v[192:195], v[64:67]
	v_mfma_f32_16x16x32_bf16 v[60:63], v[162:165], v[192:195], v[60:63]
	v_mfma_f32_16x16x32_bf16 v[56:59], v[154:157], v[200:203], v[56:59]
	v_mfma_f32_16x16x32_bf16 v[48:51], v[162:165], v[200:203], v[48:51]
	v_mfma_f32_16x16x32_bf16 v[40:43], v[154:157], v[208:211], v[40:43]
	v_mfma_f32_16x16x32_bf16 v[32:35], v[162:165], v[208:211], v[32:35]
	v_mfma_f32_16x16x32_bf16 v[24:27], v[154:157], v[230:233], v[24:27]
	v_mfma_f32_16x16x32_bf16 v[16:19], v[162:165], v[230:233], v[16:19]
	v_mfma_f32_16x16x32_bf16 v[52:55], v[172:175], v[188:191], v[52:55]
	v_mfma_f32_16x16x32_bf16 v[44:47], v[180:183], v[188:191], v[44:47]
	v_mfma_f32_16x16x32_bf16 v[36:39], v[172:175], v[196:199], v[36:39]
	v_mfma_f32_16x16x32_bf16 v[28:31], v[180:183], v[196:199], v[28:31]
	v_mfma_f32_16x16x32_bf16 v[20:23], v[172:175], v[204:207], v[20:23]
	v_mfma_f32_16x16x32_bf16 v[12:15], v[180:183], v[204:207], v[12:15]
	v_mfma_f32_16x16x32_bf16 v[8:11], v[172:175], v[226:229], v[8:11]
	v_mfma_f32_16x16x32_bf16 v[4:7], v[180:183], v[226:229], v[4:7]
	v_mfma_f32_16x16x32_bf16 v[52:55], v[176:179], v[192:195], v[52:55]
	v_mfma_f32_16x16x32_bf16 v[44:47], v[184:187], v[192:195], v[44:47]
	v_mfma_f32_16x16x32_bf16 v[36:39], v[176:179], v[200:203], v[36:39]
	v_mfma_f32_16x16x32_bf16 v[28:31], v[184:187], v[200:203], v[28:31]
	v_mfma_f32_16x16x32_bf16 v[20:23], v[176:179], v[208:211], v[20:23]
	v_mfma_f32_16x16x32_bf16 v[12:15], v[184:187], v[208:211], v[12:15]
	v_mfma_f32_16x16x32_bf16 v[8:11], v[176:179], v[230:233], v[8:11]
	v_mfma_f32_16x16x32_bf16 v[4:7], v[184:187], v[230:233], v[4:7]
	s_barrier
	s_add_u32 s20, s20, 0x100
	s_addc_u32 s21, s21, 0
	s_add_u32 s13, s13, 0x100
	s_addc_u32 s15, s15, 0
	s_cmp_ge_i32 s48, s45
	s_mov_b32 s22, s48
	s_cbranch_scc0 .LBB0_1293
	s_and_b64 vcc, exec, s[8:9]
	s_cbranch_vccz .LBB0_1296
	s_barrier

; #define PG8_STAGE(bufoff, gbase, voff) do { _Pragma("unroll") for (int _i = 0; _i < 2; ++_i) \
;         __builtin_amdgcn_global_load_lds((const unsigned*)((const char*)(gbase) + (voff)[_i]), (PG8_LAS unsigned*)(lds + (bufoff) + ldsw + _i * 8192), 16, 0, 0); } while (0)
; #define PG8_LDA(dst, b, h) do { _Pragma("unroll") for (int m = 0; m < 4; ++m) _Pragma("unroll") for (int k = 0; k < 2; ++k) dst[m][k] = *(const PG8_LAS bf16x8*)(lds + PG8_SA(b, h) + aoffk[k] + m * 2048); } while (0)
; #define PG8_LDB(dst, b, h) do { _Pragma("unroll") for (int n = 0; n < 2; ++n) _Pragma("unroll") for (int k = 0; k < 2; ++k) dst[n][k] = *(const PG8_LAS bf16x8*)(lds + PG8_SB(b, h) + boffk[k] + n * 2048); } while (0)
; #define PG8_MMA(ai, bj, At, Bt) do { __builtin_amdgcn_s_setprio(1); _Pragma("unroll") for (int m = 0; m < 4; ++m) _Pragma("unroll") for (int n = 0; n < 2; ++n) _Pragma("unroll") for (int k = 0; k < 2; ++k) \
;         acc[ai][bj][m][n] = __builtin_amdgcn_mfma_f32_16x16x32_bf16(Bt[n][k], At[m][k], acc[ai][bj][m][n], 0, 0, 0); __builtin_amdgcn_s_setprio(0); } while (0)
; #define PG8_WAIT_V(n) asm volatile("s_waitcnt vmcnt(" #n ")" ::: "memory")
; #define PG8_WAIT_L(n) asm volatile("s_waitcnt lgkmcnt(" #n ")" ::: "memory")
; #define PG8_BAR __builtin_amdgcn_s_barrier()
; template <class Epi, class Sched, bool ALIGN_EPI = false, bool SP2 = false>
; __device__ __forceinline__ void gemm_phase(PG8_LAS unsigned char* lds, const Gemm g, const Sched& S, const Epi& E) {
;     ...
;             const bool last = (t == nt - 2);
;             const char* a1 = cA + (size_t)(t + 1) * kstep;
;             const char* a2 = last ? nA : cA + (size_t)(t + 2) * kstep; const char* b2 = last ? nB : cB + (size_t)(t + 2) * kstep;
;             const char* a3 = a2 + kstep; const char* b3 = b2 + kstep;
;             if (last && has_next) S.a_ready(nxt);
;             if constexpr (SP2) {
;             PG8_LDB(B0, 0, 0); PG8_LDB(B1, 0, 1); PG8_SCHED; PG8_LDA(At, 0, 0); PG8_STAGE(PG8_SA(1, 1), a1 + hstepA, voffA);
;             PG8_WAIT_V(8); PG8_WAIT_L(0); PG8_BAR; PG8_MMA(0, 0, At, B0); PG8_MMA(0, 1, At, B1); PG8_BAR; PG8_SCHED;
;             PG8_LDA(At, 0, 1); PG8_STAGE(PG8_SB(0, 0), b2, voffB); PG8_STAGE(PG8_SB(0, 1), b2 + hstepB, voffB); PG8_STAGE(PG8_SA(0, 0), a2, voffA);
;             PG8_WAIT_V(8); PG8_WAIT_L(0); PG8_BAR; PG8_MMA(1, 0, At, B0); PG8_MMA(1, 1, At, B1); PG8_BAR; PG8_SCHED;
.LBB0_1432:
	s_add_u32 s20, s18, 0xfff80080
	s_addc_u32 s21, s19, -1
	s_add_i32 s47, 0, 0x10000
	s_cmp_eq_u32 s46, 28
	v_add_u32_e32 v142, s47, v147
	v_add_u32_e32 v151, s47, v148
	s_cselect_b32 s23, s9, s21
	s_cselect_b32 s22, s33, s20
	ds_read_b128 v[142:145], v142
	ds_read_b128 v[152:155], v151
	v_add_u32_e32 v151, s51, v147
	v_add_u32_e32 v160, s51, v148
	s_cselect_b32 s21, s7, s45
	s_cselect_b32 s20, s43, s44
	s_add_i32 s50, 0, 0x14000
	ds_read_b128 v[156:159], v151
	ds_read_b128 v[160:163], v160
	v_add_u32_e32 v151, s50, v147
	v_add_u32_e32 v168, s50, v148
	ds_read_b128 v[164:167], v151
	ds_read_b128 v[172:175], v168
	v_add_u32_e32 v151, s52, v147
	v_add_u32_e32 v168, s52, v148
	ds_read_b128 v[176:179], v151
	ds_read_b128 v[180:183], v168
	v_lshl_add_u64 v[212:213], s[18:19], 0, v[138:139]
	s_add_i32 m0, s36, 0xc000
	ds_read_b128 v[184:187], v150
	ds_read_b128 v[188:191], v150 offset:1024
	ds_read_b128 v[192:195], v150 offset:2048
	ds_read_b128 v[196:199], v150 offset:3072
	ds_read_b128 v[200:203], v150 offset:4096
	ds_read_b128 v[204:207], v150 offset:5120
	ds_read_b128 v[208:211], v150 offset:6144
	ds_read_b128 v[226:229], v150 offset:7168
	global_load_lds_dwordx4 v[212:213], off
	v_lshl_add_u64 v[212:213], s[18:19], 0, v[140:141]
	s_add_i32 m0, s36, 0xe000
	s_nop 0
	global_load_lds_dwordx4 v[212:213], off
	s_waitcnt vmcnt(8)
	s_waitcnt lgkmcnt(0)
	s_barrier
	v_mfma_f32_16x16x32_bf16 v[128:131], v[142:145], v[184:187], v[128:131]
	v_mfma_f32_16x16x32_bf16 v[120:123], v[156:159], v[184:187], v[120:123]
	v_mfma_f32_16x16x32_bf16 v[112:115], v[142:145], v[192:195], v[112:115]
	v_mfma_f32_16x16x32_bf16 v[104:107], v[156:159], v[192:195], v[104:107]
	v_mfma_f32_16x16x32_bf16 v[96:99], v[142:145], v[200:203], v[96:99]
	v_mfma_f32_16x16x32_bf16 v[88:91], v[156:159], v[200:203], v[88:91]
	v_mfma_f32_16x16x32_bf16 v[80:83], v[142:145], v[208:211], v[80:83]
	v_mfma_f32_16x16x32_bf16 v[72:75], v[156:159], v[208:211], v[72:75]
	v_mfma_f32_16x16x32_bf16 v[128:131], v[152:155], v[188:191], v[128:131]
	v_mfma_f32_16x16x32_bf16 v[120:123], v[160:163], v[188:191], v[120:123]
	v_mfma_f32_16x16x32_bf16 v[112:115], v[152:155], v[196:199], v[112:115]
	v_mfma_f32_16x16x32_bf16 v[104:107], v[160:163], v[196:199], v[104:107]
	v_mfma_f32_16x16x32_bf16 v[96:99], v[152:155], v[204:207], v[96:99]
	v_mfma_f32_16x16x32_bf16 v[88:91], v[160:163], v[204:207], v[88:91]
	v_mfma_f32_16x16x32_bf16 v[80:83], v[152:155], v[226:229], v[80:83]
	v_mfma_f32_16x16x32_bf16 v[72:75], v[160:163], v[226:229], v[72:75]
	v_mfma_f32_16x16x32_bf16 v[124:127], v[164:167], v[184:187], v[124:127]
	v_mfma_f32_16x16x32_bf16 v[116:119], v[176:179], v[184:187], v[116:119]
	v_mfma_f32_16x16x32_bf16 v[108:111], v[164:167], v[192:195], v[108:111]
	v_mfma_f32_16x16x32_bf16 v[100:103], v[176:179], v[192:195], v[100:103]
	v_mfma_f32_16x16x32_bf16 v[92:95], v[164:167], v[200:203], v[92:95]
	v_mfma_f32_16x16x32_bf16 v[84:87], v[176:179], v[200:203], v[84:87]
	v_mfma_f32_16x16x32_bf16 v[76:79], v[164:167], v[208:211], v[76:79]
	v_mfma_f32_16x16x32_bf16 v[68:71], v[176:179], v[208:211], v[68:71]
	v_mfma_f32_16x16x32_bf16 v[124:127], v[172:175], v[188:191], v[124:127]
	v_mfma_f32_16x16x32_bf16 v[116:119], v[180:183], v[188:191], v[116:119]
	v_mfma_f32_16x16x32_bf16 v[108:111], v[172:175], v[196:199], v[108:111]
	v_mfma_f32_16x16x32_bf16 v[100:103], v[180:183], v[196:199], v[100:103]
	v_mfma_f32_16x16x32_bf16 v[92:95], v[172:175], v[204:207], v[92:95]
	v_mfma_f32_16x16x32_bf16 v[84:87], v[180:183], v[204:207], v[84:87]
	v_mfma_f32_16x16x32_bf16 v[76:79], v[172:175], v[226:229], v[76:79]
	v_mfma_f32_16x16x32_bf16 v[68:71], v[180:183], v[226:229], v[68:71]
	s_barrier
	s_add_i32 s47, s47, s31
	v_lshl_add_u64 v[212:213], s[20:21], 0, v[2:3]
	s_mov_b32 m0, s47
	ds_read_b128 v[184:187], v150 offset:16384
	ds_read_b128 v[188:191], v150 offset:17408
	ds_read_b128 v[192:195], v150 offset:18432
	ds_read_b128 v[196:199], v150 offset:19456
	ds_read_b128 v[200:203], v150 offset:20480
	ds_read_b128 v[204:207], v150 offset:21504
	ds_read_b128 v[208:211], v150 offset:22528
	ds_read_b128 v[226:229], v150 offset:23552
	global_load_lds_dwordx4 v[212:213], off
	s_add_i32 m0, s47, 0x2000
	s_add_u32 s48, s20, 0x80000
	v_lshl_add_u64 v[220:221], s[20:21], 0, v[132:133]
	s_addc_u32 s49, s21, 0
	s_add_i32 s47, s50, s31
	global_load_lds_dwordx4 v[220:221], off
	v_lshl_add_u64 v[230:231], s[48:49], 0, v[2:3]
	s_mov_b32 m0, s47
	v_lshl_add_u64 v[232:233], s[22:23], 0, v[134:135]
	global_load_lds_dwordx4 v[230:231], off
	v_lshl_add_u64 v[230:231], s[48:49], 0, v[132:133]
	s_add_i32 m0, s47, 0x2000
	s_nop 0
	global_load_lds_dwordx4 v[230:231], off
	v_lshl_add_u64 v[230:231], s[22:23], 0, v[136:137]
	s_mov_b32 m0, s36
	s_nop 0
	global_load_lds_dwordx4 v[230:231], off
	s_mov_b32 m0, s37
	s_nop 0
	global_load_lds_dwordx4 v[232:233], off
	s_waitcnt vmcnt(8)
	s_waitcnt lgkmcnt(0)
	s_barrier
; #define PG8_STAGE(bufoff, gbase, voff) do { _Pragma("unroll") for (int _i = 0; _i < 2; ++_i) \
;         __builtin_amdgcn_global_load_lds((const unsigned*)((const char*)(gbase) + (voff)[_i]), (PG8_LAS unsigned*)(lds + (bufoff) + ldsw + _i * 8192), 16, 0, 0); } while (0)
; #define PG8_LDA(dst, b, h) do { _Pragma("unroll") for (int m = 0; m < 4; ++m) _Pragma("unroll") for (int k = 0; k < 2; ++k) dst[m][k] = *(const PG8_LAS bf16x8*)(lds + PG8_SA(b, h) + aoffk[k] + m * 2048); } while (0)
; #define PG8_LDB(dst, b, h) do { _Pragma("unroll") for (int n = 0; n < 2; ++n) _Pragma("unroll") for (int k = 0; k < 2; ++k) dst[n][k] = *(const PG8_LAS bf16x8*)(lds + PG8_SB(b, h) + boffk[k] + n * 2048); } while (0)
; #define PG8_MMA(ai, bj, At, Bt) do { __builtin_amdgcn_s_setprio(1); _Pragma("unroll") for (int m = 0; m < 4; ++m) _Pragma("unroll") for (int n = 0; n < 2; ++n) _Pragma("unroll") for (int k = 0; k < 2; ++k) \
;         acc[ai][bj][m][n] = __builtin_amdgcn_mfma_f32_16x16x32_bf16(Bt[n][k], At[m][k], acc[ai][bj][m][n], 0, 0, 0); __builtin_amdgcn_s_setprio(0); } while (0)
; #define PG8_WAIT_V(n) asm volatile("s_waitcnt vmcnt(" #n ")" ::: "memory")
; #define PG8_WAIT_L(n) asm volatile("s_waitcnt lgkmcnt(" #n ")" ::: "memory")
; #define PG8_BAR __builtin_amdgcn_s_barrier()
; #define PG8_SCHED __builtin_amdgcn_sched_barrier(0)
; template <class Epi, class Sched, bool ALIGN_EPI = false, bool SP2 = false>
; __device__ __forceinline__ void gemm_phase(PG8_LAS unsigned char* lds, const Gemm g, const Sched& S, const Epi& E) {
;     ...
;             PG8_WAIT_V(8); PG8_WAIT_L(0); PG8_BAR; PG8_MMA(1, 0, At, B0); PG8_MMA(1, 1, At, B1); PG8_BAR; PG8_SCHED;
;             PG8_LDB(B0, 1, 0); PG8_LDB(B1, 1, 1); PG8_SCHED; PG8_LDA(At, 1, 0); PG8_STAGE(PG8_SA(0, 1), a2 + hstepA, voffA);
;             PG8_WAIT_V(8); PG8_WAIT_L(0); PG8_BAR; PG8_MMA(0, 0, At, B0); PG8_MMA(0, 1, At, B1); PG8_BAR; PG8_SCHED;
	v_mfma_f32_16x16x32_bf16 v[64:67], v[142:145], v[184:187], v[64:67]
	v_mfma_f32_16x16x32_bf16 v[56:59], v[156:159], v[184:187], v[56:59]
	v_mfma_f32_16x16x32_bf16 v[48:51], v[142:145], v[192:195], v[48:51]
	v_mfma_f32_16x16x32_bf16 v[40:43], v[156:159], v[192:195], v[40:43]
	v_mfma_f32_16x16x32_bf16 v[32:35], v[142:145], v[200:203], v[32:35]
	v_mfma_f32_16x16x32_bf16 v[24:27], v[156:159], v[200:203], v[24:27]
	v_mfma_f32_16x16x32_bf16 v[16:19], v[142:145], v[208:211], v[16:19]
	v_mfma_f32_16x16x32_bf16 v[8:11], v[156:159], v[208:211], v[8:11]
	v_mfma_f32_16x16x32_bf16 v[64:67], v[152:155], v[188:191], v[64:67]
	v_mfma_f32_16x16x32_bf16 v[56:59], v[160:163], v[188:191], v[56:59]
	v_mfma_f32_16x16x32_bf16 v[48:51], v[152:155], v[196:199], v[48:51]
	v_mfma_f32_16x16x32_bf16 v[40:43], v[160:163], v[196:199], v[40:43]
	v_mfma_f32_16x16x32_bf16 v[32:35], v[152:155], v[204:207], v[32:35]
	v_mfma_f32_16x16x32_bf16 v[24:27], v[160:163], v[204:207], v[24:27]
	v_mfma_f32_16x16x32_bf16 v[16:19], v[152:155], v[226:229], v[16:19]
	v_mfma_f32_16x16x32_bf16 v[8:11], v[160:163], v[226:229], v[8:11]
	v_mfma_f32_16x16x32_bf16 v[60:63], v[164:167], v[184:187], v[60:63]
	v_mfma_f32_16x16x32_bf16 v[52:55], v[176:179], v[184:187], v[52:55]
	v_mfma_f32_16x16x32_bf16 v[44:47], v[164:167], v[192:195], v[44:47]
	v_mfma_f32_16x16x32_bf16 v[36:39], v[176:179], v[192:195], v[36:39]
	v_mfma_f32_16x16x32_bf16 v[28:31], v[164:167], v[200:203], v[28:31]
	v_mfma_f32_16x16x32_bf16 v[20:23], v[176:179], v[200:203], v[20:23]
	v_mfma_f32_16x16x32_bf16 v[12:15], v[164:167], v[208:211], v[12:15]
	v_mfma_f32_16x16x32_bf16 v[4:7], v[176:179], v[208:211], v[4:7]
	v_mfma_f32_16x16x32_bf16 v[60:63], v[172:175], v[188:191], v[60:63]
	v_mfma_f32_16x16x32_bf16 v[52:55], v[180:183], v[188:191], v[52:55]
	v_mfma_f32_16x16x32_bf16 v[44:47], v[172:175], v[196:199], v[44:47]
	v_mfma_f32_16x16x32_bf16 v[36:39], v[180:183], v[196:199], v[36:39]
	v_mfma_f32_16x16x32_bf16 v[28:31], v[172:175], v[204:207], v[28:31]
	v_mfma_f32_16x16x32_bf16 v[20:23], v[180:183], v[204:207], v[20:23]
	v_mfma_f32_16x16x32_bf16 v[12:15], v[172:175], v[226:229], v[12:15]
	v_mfma_f32_16x16x32_bf16 v[4:7], v[180:183], v[226:229], v[4:7]
	s_barrier
	s_add_i32 s47, 0, 0x18000
	v_add_u32_e32 v142, s47, v147
	v_add_u32_e32 v151, s47, v148
	ds_read_b128 v[142:145], v142
	ds_read_b128 v[152:155], v151
	v_add_u32_e32 v151, s53, v147
	v_add_u32_e32 v160, s53, v148
	s_add_i32 s48, 0, 0x1c000
	ds_read_b128 v[156:159], v151
	ds_read_b128 v[160:163], v160
	v_add_u32_e32 v151, s48, v147
	v_add_u32_e32 v168, s48, v148
	ds_read_b128 v[164:167], v151
	ds_read_b128 v[172:175], v168
	v_add_u32_e32 v151, s54, v147
	v_add_u32_e32 v168, s54, v148
	ds_read_b128 v[176:179], v151
	ds_read_b128 v[180:183], v168
	s_add_u32 s22, s22, 0x80000
	s_addc_u32 s23, s23, 0
	s_mov_b32 m0, s38
	v_lshl_add_u64 v[234:235], s[22:23], 0, v[136:137]
	ds_read_b128 v[184:187], v150 offset:32768
	ds_read_b128 v[188:191], v150 offset:33792
	ds_read_b128 v[192:195], v150 offset:34816
	ds_read_b128 v[196:199], v150 offset:35840
	ds_read_b128 v[200:203], v150 offset:36864
	ds_read_b128 v[204:207], v150 offset:37888
	ds_read_b128 v[208:211], v150 offset:38912
	ds_read_b128 v[226:229], v150 offset:39936
	global_load_lds_dwordx4 v[234:235], off
	v_lshl_add_u64 v[234:235], s[22:23], 0, v[134:135]
	s_mov_b32 m0, s39
	s_nop 0
	global_load_lds_dwordx4 v[234:235], off
	s_waitcnt vmcnt(8)
	s_waitcnt lgkmcnt(0)
	s_barrier
	v_mfma_f32_16x16x32_bf16 v[128:131], v[142:145], v[184:187], v[128:131]
	v_mfma_f32_16x16x32_bf16 v[120:123], v[156:159], v[184:187], v[120:123]
	v_mfma_f32_16x16x32_bf16 v[112:115], v[142:145], v[192:195], v[112:115]
	v_mfma_f32_16x16x32_bf16 v[104:107], v[156:159], v[192:195], v[104:107]
	v_mfma_f32_16x16x32_bf16 v[96:99], v[142:145], v[200:203], v[96:99]
	v_mfma_f32_16x16x32_bf16 v[88:91], v[156:159], v[200:203], v[88:91]
	v_mfma_f32_16x16x32_bf16 v[80:83], v[142:145], v[208:211], v[80:83]
	v_mfma_f32_16x16x32_bf16 v[72:75], v[156:159], v[208:211], v[72:75]
	v_mfma_f32_16x16x32_bf16 v[128:131], v[152:155], v[188:191], v[128:131]
	v_mfma_f32_16x16x32_bf16 v[120:123], v[160:163], v[188:191], v[120:123]
	v_mfma_f32_16x16x32_bf16 v[112:115], v[152:155], v[196:199], v[112:115]
	v_mfma_f32_16x16x32_bf16 v[104:107], v[160:163], v[196:199], v[104:107]
	v_mfma_f32_16x16x32_bf16 v[96:99], v[152:155], v[204:207], v[96:99]
	v_mfma_f32_16x16x32_bf16 v[88:91], v[160:163], v[204:207], v[88:91]
	v_mfma_f32_16x16x32_bf16 v[80:83], v[152:155], v[226:229], v[80:83]
	v_mfma_f32_16x16x32_bf16 v[72:75], v[160:163], v[226:229], v[72:75]
	v_mfma_f32_16x16x32_bf16 v[124:127], v[164:167], v[184:187], v[124:127]
	v_mfma_f32_16x16x32_bf16 v[116:119], v[176:179], v[184:187], v[116:119]
	v_mfma_f32_16x16x32_bf16 v[108:111], v[164:167], v[192:195], v[108:111]
	v_mfma_f32_16x16x32_bf16 v[100:103], v[176:179], v[192:195], v[100:103]
	v_mfma_f32_16x16x32_bf16 v[92:95], v[164:167], v[200:203], v[92:95]
	v_mfma_f32_16x16x32_bf16 v[84:87], v[176:179], v[200:203], v[84:87]
	v_mfma_f32_16x16x32_bf16 v[76:79], v[164:167], v[208:211], v[76:79]
	v_mfma_f32_16x16x32_bf16 v[68:71], v[176:179], v[208:211], v[68:71]
	v_mfma_f32_16x16x32_bf16 v[124:127], v[172:175], v[188:191], v[124:127]
	v_mfma_f32_16x16x32_bf16 v[116:119], v[180:183], v[188:191], v[116:119]
	v_mfma_f32_16x16x32_bf16 v[108:111], v[172:175], v[196:199], v[108:111]
	v_mfma_f32_16x16x32_bf16 v[100:103], v[180:183], v[196:199], v[100:103]
	v_mfma_f32_16x16x32_bf16 v[92:95], v[172:175], v[204:207], v[92:95]
	v_mfma_f32_16x16x32_bf16 v[84:87], v[180:183], v[204:207], v[84:87]
	v_mfma_f32_16x16x32_bf16 v[76:79], v[172:175], v[226:229], v[76:79]
	v_mfma_f32_16x16x32_bf16 v[68:71], v[180:183], v[226:229], v[68:71]
	s_barrier
; #define PG8_STAGE(bufoff, gbase, voff) do { _Pragma("unroll") for (int _i = 0; _i < 2; ++_i) \
;         __builtin_amdgcn_global_load_lds((const unsigned*)((const char*)(gbase) + (voff)[_i]), (PG8_LAS unsigned*)(lds + (bufoff) + ldsw + _i * 8192), 16, 0, 0); } while (0)
; #define PG8_LDA(dst, b, h) do { _Pragma("unroll") for (int m = 0; m < 4; ++m) _Pragma("unroll") for (int k = 0; k < 2; ++k) dst[m][k] = *(const PG8_LAS bf16x8*)(lds + PG8_SA(b, h) + aoffk[k] + m * 2048); } while (0)
; #define PG8_MMA(ai, bj, At, Bt) do { __builtin_amdgcn_s_setprio(1); _Pragma("unroll") for (int m = 0; m < 4; ++m) _Pragma("unroll") for (int n = 0; n < 2; ++n) _Pragma("unroll") for (int k = 0; k < 2; ++k) \
;         acc[ai][bj][m][n] = __builtin_amdgcn_mfma_f32_16x16x32_bf16(Bt[n][k], At[m][k], acc[ai][bj][m][n], 0, 0, 0); __builtin_amdgcn_s_setprio(0); } while (0)
; #define PG8_WAIT_V(n) asm volatile("s_waitcnt vmcnt(" #n ")" ::: "memory")
; #define PG8_WAIT_L(n) asm volatile("s_waitcnt lgkmcnt(" #n ")" ::: "memory")
; #define PG8_BAR __builtin_amdgcn_s_barrier()
; #define PG8_SCHED __builtin_amdgcn_sched_barrier(0)
; template <class Epi, class Sched, bool ALIGN_EPI = false, bool SP2 = false>
; __device__ __forceinline__ void gemm_phase(PG8_LAS unsigned char* lds, const Gemm g, const Sched& S, const Epi& E) {
;     ...
;             PG8_LDA(At, 1, 1); PG8_STAGE(PG8_SB(1, 0), b3, voffB); PG8_STAGE(PG8_SB(1, 1), b3 + hstepB, voffB); PG8_STAGE(PG8_SA(1, 0), a3, voffA);
;             PG8_WAIT_V(8); PG8_WAIT_L(0); PG8_BAR; PG8_MMA(1, 0, At, B0); PG8_MMA(1, 1, At, B1); PG8_BAR; PG8_SCHED;
	s_add_i32 s22, s47, s31
	v_lshl_add_u64 v[212:213], v[212:213], 0, s[56:57]
	s_mov_b32 m0, s22
	ds_read_b128 v[184:187], v150 offset:49152
	ds_read_b128 v[188:191], v150 offset:50176
	ds_read_b128 v[192:195], v150 offset:51200
	ds_read_b128 v[196:199], v150 offset:52224
	ds_read_b128 v[200:203], v150 offset:53248
	ds_read_b128 v[204:207], v150 offset:54272
	ds_read_b128 v[208:211], v150 offset:55296
	ds_read_b128 v[226:229], v150 offset:56320
	global_load_lds_dwordx4 v[212:213], off
	s_add_i32 m0, s22, 0x2000
	s_add_u32 s20, s20, 0x80080
	v_lshl_add_u64 v[212:213], v[220:221], 0, s[56:57]
	s_addc_u32 s21, s21, 0
	s_add_i32 s22, s48, s31
	global_load_lds_dwordx4 v[212:213], off
	v_lshl_add_u64 v[212:213], s[20:21], 0, v[2:3]
	s_mov_b32 m0, s22
	s_nop 0
	global_load_lds_dwordx4 v[212:213], off
	v_lshl_add_u64 v[212:213], s[20:21], 0, v[132:133]
	s_add_i32 m0, s22, 0x2000
	s_nop 0
	global_load_lds_dwordx4 v[212:213], off
	v_lshl_add_u64 v[212:213], v[230:231], 0, s[56:57]
	s_mov_b32 m0, s40
	s_nop 0
	global_load_lds_dwordx4 v[212:213], off
	v_lshl_add_u64 v[212:213], v[232:233], 0, s[56:57]
	s_mov_b32 m0, s41
	s_nop 0
	global_load_lds_dwordx4 v[212:213], off
	s_waitcnt vmcnt(8)
	s_waitcnt lgkmcnt(0)
	s_barrier
	v_mfma_f32_16x16x32_bf16 v[64:67], v[142:145], v[184:187], v[64:67]
	v_mfma_f32_16x16x32_bf16 v[56:59], v[156:159], v[184:187], v[56:59]
	v_mfma_f32_16x16x32_bf16 v[48:51], v[142:145], v[192:195], v[48:51]
	v_mfma_f32_16x16x32_bf16 v[40:43], v[156:159], v[192:195], v[40:43]
	v_mfma_f32_16x16x32_bf16 v[32:35], v[142:145], v[200:203], v[32:35]
	v_mfma_f32_16x16x32_bf16 v[24:27], v[156:159], v[200:203], v[24:27]
	v_mfma_f32_16x16x32_bf16 v[16:19], v[142:145], v[208:211], v[16:19]
	v_mfma_f32_16x16x32_bf16 v[8:11], v[156:159], v[208:211], v[8:11]
	v_mfma_f32_16x16x32_bf16 v[64:67], v[152:155], v[188:191], v[64:67]
	v_mfma_f32_16x16x32_bf16 v[56:59], v[160:163], v[188:191], v[56:59]
	v_mfma_f32_16x16x32_bf16 v[48:51], v[152:155], v[196:199], v[48:51]
	v_mfma_f32_16x16x32_bf16 v[40:43], v[160:163], v[196:199], v[40:43]
	v_mfma_f32_16x16x32_bf16 v[32:35], v[152:155], v[204:207], v[32:35]
	v_mfma_f32_16x16x32_bf16 v[24:27], v[160:163], v[204:207], v[24:27]
	v_mfma_f32_16x16x32_bf16 v[16:19], v[152:155], v[226:229], v[16:19]
	v_mfma_f32_16x16x32_bf16 v[8:11], v[160:163], v[226:229], v[8:11]
	v_mfma_f32_16x16x32_bf16 v[60:63], v[164:167], v[184:187], v[60:63]
	v_mfma_f32_16x16x32_bf16 v[52:55], v[176:179], v[184:187], v[52:55]
	v_mfma_f32_16x16x32_bf16 v[44:47], v[164:167], v[192:195], v[44:47]
	v_mfma_f32_16x16x32_bf16 v[36:39], v[176:179], v[192:195], v[36:39]
	v_mfma_f32_16x16x32_bf16 v[28:31], v[164:167], v[200:203], v[28:31]
	v_mfma_f32_16x16x32_bf16 v[20:23], v[176:179], v[200:203], v[20:23]
	v_mfma_f32_16x16x32_bf16 v[12:15], v[164:167], v[208:211], v[12:15]
	v_mfma_f32_16x16x32_bf16 v[4:7], v[176:179], v[208:211], v[4:7]
	v_mfma_f32_16x16x32_bf16 v[60:63], v[172:175], v[188:191], v[60:63]
	v_mfma_f32_16x16x32_bf16 v[52:55], v[180:183], v[188:191], v[52:55]
	v_mfma_f32_16x16x32_bf16 v[44:47], v[172:175], v[196:199], v[44:47]
	v_mfma_f32_16x16x32_bf16 v[36:39], v[180:183], v[196:199], v[36:39]
	v_mfma_f32_16x16x32_bf16 v[28:31], v[172:175], v[204:207], v[28:31]
	v_mfma_f32_16x16x32_bf16 v[20:23], v[180:183], v[204:207], v[20:23]
	v_mfma_f32_16x16x32_bf16 v[12:15], v[172:175], v[226:229], v[12:15]
	v_mfma_f32_16x16x32_bf16 v[4:7], v[180:183], v[226:229], v[4:7]
	s_barrier
	s_add_i32 s46, s46, 2
	s_add_u32 s18, s18, 0x100
	s_addc_u32 s19, s19, 0
	s_add_u32 s44, s44, 0x100
	s_addc_u32 s45, s45, 0
	s_cmp_gt_u32 s46, 29
	s_cbranch_scc0 .LBB0_1432
	s_and_b64 vcc, exec, s[4:5]
	s_cbranch_vccz .LBB0_1435
	s_barrier

; #define PG8_STAGE(bufoff, gbase, voff) do { _Pragma("unroll") for (int _i = 0; _i < 2; ++_i) \
;         __builtin_amdgcn_global_load_lds((const unsigned*)((const char*)(gbase) + (voff)[_i]), (PG8_LAS unsigned*)(lds + (bufoff) + ldsw + _i * 8192), 16, 0, 0); } while (0)
; #define PG8_LDA(dst, b, h) do { _Pragma("unroll") for (int m = 0; m < 4; ++m) _Pragma("unroll") for (int k = 0; k < 2; ++k) dst[m][k] = *(const PG8_LAS bf16x8*)(lds + PG8_SA(b, h) + aoffk[k] + m * 2048); } while (0)
; #define PG8_LDB(dst, b, h) do { _Pragma("unroll") for (int n = 0; n < 2; ++n) _Pragma("unroll") for (int k = 0; k < 2; ++k) dst[n][k] = *(const PG8_LAS bf16x8*)(lds + PG8_SB(b, h) + boffk[k] + n * 2048); } while (0)
; #define PG8_MMA(ai, bj, At, Bt) do { __builtin_amdgcn_s_setprio(1); _Pragma("unroll") for (int m = 0; m < 4; ++m) _Pragma("unroll") for (int n = 0; n < 2; ++n) _Pragma("unroll") for (int k = 0; k < 2; ++k) \
;         acc[ai][bj][m][n] = __builtin_amdgcn_mfma_f32_16x16x32_bf16(Bt[n][k], At[m][k], acc[ai][bj][m][n], 0, 0, 0); __builtin_amdgcn_s_setprio(0); } while (0)
; #define PG8_WAIT_V(n) asm volatile("s_waitcnt vmcnt(" #n ")" ::: "memory")
; #define PG8_WAIT_L(n) asm volatile("s_waitcnt lgkmcnt(" #n ")" ::: "memory")
; #define PG8_BAR __builtin_amdgcn_s_barrier()
; template <class Epi, class Sched, bool ALIGN_EPI = false, bool SP2 = false>
; __device__ __forceinline__ void gemm_phase(PG8_LAS unsigned char* lds, const Gemm g, const Sched& S, const Epi& E) {
;     ...
;             const bool last = (t == nt - 2);
;             const char* a1 = cA + (size_t)(t + 1) * kstep;
;             const char* a2 = last ? nA : cA + (size_t)(t + 2) * kstep; const char* b2 = last ? nB : cB + (size_t)(t + 2) * kstep;
;             const char* a3 = a2 + kstep; const char* b3 = b2 + kstep;
;             if (last && has_next) S.a_ready(nxt);
;             if constexpr (SP2) {
;             PG8_LDB(B0, 0, 0); PG8_LDB(B1, 0, 1); PG8_SCHED; PG8_LDA(At, 0, 0); PG8_STAGE(PG8_SA(1, 1), a1 + hstepA, voffA);
;             PG8_WAIT_V(8); PG8_WAIT_L(0); PG8_BAR; PG8_MMA(0, 0, At, B0); PG8_MMA(0, 1, At, B1); PG8_BAR; PG8_SCHED;
;             PG8_LDA(At, 0, 1); PG8_STAGE(PG8_SB(0, 0), b2, voffB); PG8_STAGE(PG8_SB(0, 1), b2 + hstepB, voffB); PG8_STAGE(PG8_SA(0, 0), a2, voffA);
;             PG8_WAIT_V(8); PG8_WAIT_L(0); PG8_BAR; PG8_MMA(1, 0, At, B0); PG8_MMA(1, 1, At, B1); PG8_BAR; PG8_SCHED;
.LBB0_1592:
	s_add_i32 s50, s16, 2
	s_add_u32 s14, s12, 0x100
	s_addc_u32 s15, s13, 0
	s_add_i32 s51, 0, 0x10000
	s_cmp_eq_u32 s7, s16
	v_add_u32_e32 v142, s51, v145
	s_cselect_b32 s19, s9, s15
	s_cselect_b32 s18, s8, s14
	v_add_u32_e32 v143, s51, v146
	ds_read_b128 v[150:153], v142
	ds_read_b128 v[154:157], v143
	v_add_u32_e32 v142, s53, v145
	s_cselect_b32 s17, s11, s49
	s_cselect_b32 s16, s10, s48
	s_add_i32 s52, 0, 0x14000
	v_add_u32_e32 v143, s53, v146
	ds_read_b128 v[158:161], v142
	ds_read_b128 v[162:165], v143
	v_add_u32_e32 v142, s52, v145
	v_add_u32_e32 v143, s52, v146
	ds_read_b128 v[172:175], v142
	ds_read_b128 v[176:179], v143
	v_add_u32_e32 v142, s54, v145
	v_add_u32_e32 v143, s54, v146
	ds_read_b128 v[180:183], v142
	ds_read_b128 v[184:187], v143
	v_lshl_add_u64 v[142:143], s[12:13], 0, v[138:139]
	s_add_i32 m0, s26, 0xc000
	ds_read_b128 v[188:191], v148
	ds_read_b128 v[192:195], v148 offset:1024
	ds_read_b128 v[196:199], v148 offset:2048
	ds_read_b128 v[200:203], v148 offset:3072
	ds_read_b128 v[204:207], v148 offset:4096
	ds_read_b128 v[208:211], v148 offset:5120
	ds_read_b128 v[226:229], v148 offset:6144
	ds_read_b128 v[230:233], v148 offset:7168
	global_load_lds_dwordx4 v[142:143], off
	v_lshl_add_u64 v[142:143], s[12:13], 0, v[140:141]
	s_add_i32 m0, s26, 0xe000
	s_nop 0
	global_load_lds_dwordx4 v[142:143], off
	s_waitcnt vmcnt(8)
	s_waitcnt lgkmcnt(0)
	s_barrier
	v_mfma_f32_16x16x32_bf16 v[128:131], v[150:153], v[188:191], v[128:131]
	v_mfma_f32_16x16x32_bf16 v[124:127], v[158:161], v[188:191], v[124:127]
	v_mfma_f32_16x16x32_bf16 v[120:123], v[150:153], v[196:199], v[120:123]
	v_mfma_f32_16x16x32_bf16 v[112:115], v[158:161], v[196:199], v[112:115]
	v_mfma_f32_16x16x32_bf16 v[104:107], v[150:153], v[204:207], v[104:107]
	v_mfma_f32_16x16x32_bf16 v[96:99], v[158:161], v[204:207], v[96:99]
	v_mfma_f32_16x16x32_bf16 v[88:91], v[150:153], v[226:229], v[88:91]
	v_mfma_f32_16x16x32_bf16 v[80:83], v[158:161], v[226:229], v[80:83]
	v_mfma_f32_16x16x32_bf16 v[128:131], v[154:157], v[192:195], v[128:131]
	v_mfma_f32_16x16x32_bf16 v[124:127], v[162:165], v[192:195], v[124:127]
	v_mfma_f32_16x16x32_bf16 v[120:123], v[154:157], v[200:203], v[120:123]
	v_mfma_f32_16x16x32_bf16 v[112:115], v[162:165], v[200:203], v[112:115]
	v_mfma_f32_16x16x32_bf16 v[104:107], v[154:157], v[208:211], v[104:107]
	v_mfma_f32_16x16x32_bf16 v[96:99], v[162:165], v[208:211], v[96:99]
	v_mfma_f32_16x16x32_bf16 v[88:91], v[154:157], v[230:233], v[88:91]
	v_mfma_f32_16x16x32_bf16 v[80:83], v[162:165], v[230:233], v[80:83]
	v_mfma_f32_16x16x32_bf16 v[116:119], v[172:175], v[188:191], v[116:119]
	v_mfma_f32_16x16x32_bf16 v[108:111], v[180:183], v[188:191], v[108:111]
	v_mfma_f32_16x16x32_bf16 v[100:103], v[172:175], v[196:199], v[100:103]
	v_mfma_f32_16x16x32_bf16 v[92:95], v[180:183], v[196:199], v[92:95]
	v_mfma_f32_16x16x32_bf16 v[84:87], v[172:175], v[204:207], v[84:87]
	v_mfma_f32_16x16x32_bf16 v[76:79], v[180:183], v[204:207], v[76:79]
	v_mfma_f32_16x16x32_bf16 v[72:75], v[172:175], v[226:229], v[72:75]
	v_mfma_f32_16x16x32_bf16 v[68:71], v[180:183], v[226:229], v[68:71]
	v_mfma_f32_16x16x32_bf16 v[116:119], v[176:179], v[192:195], v[116:119]
	v_mfma_f32_16x16x32_bf16 v[108:111], v[184:187], v[192:195], v[108:111]
	v_mfma_f32_16x16x32_bf16 v[100:103], v[176:179], v[200:203], v[100:103]
	v_mfma_f32_16x16x32_bf16 v[92:95], v[184:187], v[200:203], v[92:95]
	v_mfma_f32_16x16x32_bf16 v[84:87], v[176:179], v[208:211], v[84:87]
	v_mfma_f32_16x16x32_bf16 v[76:79], v[184:187], v[208:211], v[76:79]
	v_mfma_f32_16x16x32_bf16 v[72:75], v[176:179], v[230:233], v[72:75]
	v_mfma_f32_16x16x32_bf16 v[68:71], v[184:187], v[230:233], v[68:71]
	s_barrier
	s_add_i32 s12, s51, s25
	v_lshl_add_u64 v[142:143], s[16:17], 0, v[2:3]
	s_mov_b32 m0, s12
	ds_read_b128 v[188:191], v148 offset:16384
	ds_read_b128 v[192:195], v148 offset:17408
	ds_read_b128 v[196:199], v148 offset:18432
	ds_read_b128 v[200:203], v148 offset:19456
	ds_read_b128 v[204:207], v148 offset:20480
	ds_read_b128 v[208:211], v148 offset:21504
	ds_read_b128 v[226:229], v148 offset:22528
	ds_read_b128 v[230:233], v148 offset:23552
	global_load_lds_dwordx4 v[142:143], off
	s_add_i32 m0, s12, 0x2000
	s_add_u32 s12, s16, 0x160000
	v_lshl_add_u64 v[166:167], s[16:17], 0, v[136:137]
	s_addc_u32 s13, s17, 0
	s_add_i32 s51, s52, s25
	global_load_lds_dwordx4 v[166:167], off
	v_lshl_add_u64 v[212:213], s[12:13], 0, v[2:3]
	s_mov_b32 m0, s51
	v_lshl_add_u64 v[220:221], s[18:19], 0, v[134:135]
	global_load_lds_dwordx4 v[212:213], off
	v_lshl_add_u64 v[212:213], s[12:13], 0, v[136:137]
	s_add_i32 m0, s51, 0x2000
	s_nop 0
	global_load_lds_dwordx4 v[212:213], off
	v_lshl_add_u64 v[212:213], s[18:19], 0, v[132:133]
	s_mov_b32 m0, s26
	s_nop 0
	global_load_lds_dwordx4 v[212:213], off
	s_mov_b32 m0, s27
	s_nop 0
	global_load_lds_dwordx4 v[220:221], off
	s_waitcnt vmcnt(8)
	s_waitcnt lgkmcnt(0)
	s_barrier
; #define PG8_STAGE(bufoff, gbase, voff) do { _Pragma("unroll") for (int _i = 0; _i < 2; ++_i) \
;         __builtin_amdgcn_global_load_lds((const unsigned*)((const char*)(gbase) + (voff)[_i]), (PG8_LAS unsigned*)(lds + (bufoff) + ldsw + _i * 8192), 16, 0, 0); } while (0)
; #define PG8_LDA(dst, b, h) do { _Pragma("unroll") for (int m = 0; m < 4; ++m) _Pragma("unroll") for (int k = 0; k < 2; ++k) dst[m][k] = *(const PG8_LAS bf16x8*)(lds + PG8_SA(b, h) + aoffk[k] + m * 2048); } while (0)
; #define PG8_LDB(dst, b, h) do { _Pragma("unroll") for (int n = 0; n < 2; ++n) _Pragma("unroll") for (int k = 0; k < 2; ++k) dst[n][k] = *(const PG8_LAS bf16x8*)(lds + PG8_SB(b, h) + boffk[k] + n * 2048); } while (0)
; #define PG8_MMA(ai, bj, At, Bt) do { __builtin_amdgcn_s_setprio(1); _Pragma("unroll") for (int m = 0; m < 4; ++m) _Pragma("unroll") for (int n = 0; n < 2; ++n) _Pragma("unroll") for (int k = 0; k < 2; ++k) \
;         acc[ai][bj][m][n] = __builtin_amdgcn_mfma_f32_16x16x32_bf16(Bt[n][k], At[m][k], acc[ai][bj][m][n], 0, 0, 0); __builtin_amdgcn_s_setprio(0); } while (0)
; #define PG8_WAIT_V(n) asm volatile("s_waitcnt vmcnt(" #n ")" ::: "memory")
; #define PG8_WAIT_L(n) asm volatile("s_waitcnt lgkmcnt(" #n ")" ::: "memory")
; #define PG8_BAR __builtin_amdgcn_s_barrier()
; #define PG8_SCHED __builtin_amdgcn_sched_barrier(0)
; template <class Epi, class Sched, bool ALIGN_EPI = false, bool SP2 = false>
; __device__ __forceinline__ void gemm_phase(PG8_LAS unsigned char* lds, const Gemm g, const Sched& S, const Epi& E) {
;     ...
;             PG8_WAIT_V(8); PG8_WAIT_L(0); PG8_BAR; PG8_MMA(1, 0, At, B0); PG8_MMA(1, 1, At, B1); PG8_BAR; PG8_SCHED;
;             PG8_LDB(B0, 1, 0); PG8_LDB(B1, 1, 1); PG8_SCHED; PG8_LDA(At, 1, 0); PG8_STAGE(PG8_SA(0, 1), a2 + hstepA, voffA);
;             PG8_WAIT_V(8); PG8_WAIT_L(0); PG8_BAR; PG8_MMA(0, 0, At, B0); PG8_MMA(0, 1, At, B1); PG8_BAR; PG8_SCHED;
	v_mfma_f32_16x16x32_bf16 v[64:67], v[150:153], v[188:191], v[64:67]
	v_mfma_f32_16x16x32_bf16 v[60:63], v[158:161], v[188:191], v[60:63]
	v_mfma_f32_16x16x32_bf16 v[56:59], v[150:153], v[196:199], v[56:59]
	v_mfma_f32_16x16x32_bf16 v[48:51], v[158:161], v[196:199], v[48:51]
	v_mfma_f32_16x16x32_bf16 v[40:43], v[150:153], v[204:207], v[40:43]
	v_mfma_f32_16x16x32_bf16 v[32:35], v[158:161], v[204:207], v[32:35]
	v_mfma_f32_16x16x32_bf16 v[24:27], v[150:153], v[226:229], v[24:27]
	v_mfma_f32_16x16x32_bf16 v[16:19], v[158:161], v[226:229], v[16:19]
	v_mfma_f32_16x16x32_bf16 v[64:67], v[154:157], v[192:195], v[64:67]
	v_mfma_f32_16x16x32_bf16 v[60:63], v[162:165], v[192:195], v[60:63]
	v_mfma_f32_16x16x32_bf16 v[56:59], v[154:157], v[200:203], v[56:59]
	v_mfma_f32_16x16x32_bf16 v[48:51], v[162:165], v[200:203], v[48:51]
	v_mfma_f32_16x16x32_bf16 v[40:43], v[154:157], v[208:211], v[40:43]
	v_mfma_f32_16x16x32_bf16 v[32:35], v[162:165], v[208:211], v[32:35]
	v_mfma_f32_16x16x32_bf16 v[24:27], v[154:157], v[230:233], v[24:27]
	v_mfma_f32_16x16x32_bf16 v[16:19], v[162:165], v[230:233], v[16:19]
	v_mfma_f32_16x16x32_bf16 v[52:55], v[172:175], v[188:191], v[52:55]
	v_mfma_f32_16x16x32_bf16 v[44:47], v[180:183], v[188:191], v[44:47]
	v_mfma_f32_16x16x32_bf16 v[36:39], v[172:175], v[196:199], v[36:39]
	v_mfma_f32_16x16x32_bf16 v[28:31], v[180:183], v[196:199], v[28:31]
	v_mfma_f32_16x16x32_bf16 v[20:23], v[172:175], v[204:207], v[20:23]
	v_mfma_f32_16x16x32_bf16 v[12:15], v[180:183], v[204:207], v[12:15]
	v_mfma_f32_16x16x32_bf16 v[8:11], v[172:175], v[226:229], v[8:11]
	v_mfma_f32_16x16x32_bf16 v[4:7], v[180:183], v[226:229], v[4:7]
	v_mfma_f32_16x16x32_bf16 v[52:55], v[176:179], v[192:195], v[52:55]
	v_mfma_f32_16x16x32_bf16 v[44:47], v[184:187], v[192:195], v[44:47]
	v_mfma_f32_16x16x32_bf16 v[36:39], v[176:179], v[200:203], v[36:39]
	v_mfma_f32_16x16x32_bf16 v[28:31], v[184:187], v[200:203], v[28:31]
	v_mfma_f32_16x16x32_bf16 v[20:23], v[176:179], v[208:211], v[20:23]
	v_mfma_f32_16x16x32_bf16 v[12:15], v[184:187], v[208:211], v[12:15]
	v_mfma_f32_16x16x32_bf16 v[8:11], v[176:179], v[230:233], v[8:11]
	v_mfma_f32_16x16x32_bf16 v[4:7], v[184:187], v[230:233], v[4:7]
	s_barrier
	s_add_i32 s51, 0, 0x18000
	v_add_u32_e32 v149, s51, v145
	v_add_u32_e32 v154, s51, v146
	ds_read_b128 v[150:153], v149
	ds_read_b128 v[154:157], v154
	v_add_u32_e32 v149, s55, v145
	v_add_u32_e32 v162, s55, v146
	s_add_i32 s52, 0, 0x1c000
	ds_read_b128 v[158:161], v149
	ds_read_b128 v[162:165], v162
	v_add_u32_e32 v149, s52, v145
	v_add_u32_e32 v168, s52, v146
	ds_read_b128 v[172:175], v149
	ds_read_b128 v[176:179], v168
	v_add_u32_e32 v149, s56, v145
	v_add_u32_e32 v168, s56, v146
	ds_read_b128 v[180:183], v149
	ds_read_b128 v[184:187], v168
	s_add_u32 s12, s18, 0x160000
	s_addc_u32 s13, s19, 0
	s_mov_b32 m0, s28
	v_lshl_add_u64 v[234:235], s[12:13], 0, v[132:133]
	ds_read_b128 v[188:191], v148 offset:32768
	ds_read_b128 v[192:195], v148 offset:33792
	ds_read_b128 v[196:199], v148 offset:34816
	ds_read_b128 v[200:203], v148 offset:35840
	ds_read_b128 v[204:207], v148 offset:36864
	ds_read_b128 v[208:211], v148 offset:37888
	ds_read_b128 v[226:229], v148 offset:38912
	ds_read_b128 v[230:233], v148 offset:39936
	global_load_lds_dwordx4 v[234:235], off
	v_lshl_add_u64 v[234:235], s[12:13], 0, v[134:135]
	s_mov_b32 m0, s29
	s_nop 0
	global_load_lds_dwordx4 v[234:235], off
	s_waitcnt vmcnt(8)
	s_waitcnt lgkmcnt(0)
	s_barrier
	v_mfma_f32_16x16x32_bf16 v[128:131], v[150:153], v[188:191], v[128:131]
	v_mfma_f32_16x16x32_bf16 v[124:127], v[158:161], v[188:191], v[124:127]
	v_mfma_f32_16x16x32_bf16 v[120:123], v[150:153], v[196:199], v[120:123]
	v_mfma_f32_16x16x32_bf16 v[112:115], v[158:161], v[196:199], v[112:115]
	v_mfma_f32_16x16x32_bf16 v[104:107], v[150:153], v[204:207], v[104:107]
	v_mfma_f32_16x16x32_bf16 v[96:99], v[158:161], v[204:207], v[96:99]
	v_mfma_f32_16x16x32_bf16 v[88:91], v[150:153], v[226:229], v[88:91]
	v_mfma_f32_16x16x32_bf16 v[80:83], v[158:161], v[226:229], v[80:83]
	v_mfma_f32_16x16x32_bf16 v[128:131], v[154:157], v[192:195], v[128:131]
	v_mfma_f32_16x16x32_bf16 v[124:127], v[162:165], v[192:195], v[124:127]
	v_mfma_f32_16x16x32_bf16 v[120:123], v[154:157], v[200:203], v[120:123]
	v_mfma_f32_16x16x32_bf16 v[112:115], v[162:165], v[200:203], v[112:115]
	v_mfma_f32_16x16x32_bf16 v[104:107], v[154:157], v[208:211], v[104:107]
	v_mfma_f32_16x16x32_bf16 v[96:99], v[162:165], v[208:211], v[96:99]
	v_mfma_f32_16x16x32_bf16 v[88:91], v[154:157], v[230:233], v[88:91]
	v_mfma_f32_16x16x32_bf16 v[80:83], v[162:165], v[230:233], v[80:83]
	v_mfma_f32_16x16x32_bf16 v[116:119], v[172:175], v[188:191], v[116:119]
	v_mfma_f32_16x16x32_bf16 v[108:111], v[180:183], v[188:191], v[108:111]
	v_mfma_f32_16x16x32_bf16 v[100:103], v[172:175], v[196:199], v[100:103]
	v_mfma_f32_16x16x32_bf16 v[92:95], v[180:183], v[196:199], v[92:95]
	v_mfma_f32_16x16x32_bf16 v[84:87], v[172:175], v[204:207], v[84:87]
	v_mfma_f32_16x16x32_bf16 v[76:79], v[180:183], v[204:207], v[76:79]
	v_mfma_f32_16x16x32_bf16 v[72:75], v[172:175], v[226:229], v[72:75]
	v_mfma_f32_16x16x32_bf16 v[68:71], v[180:183], v[226:229], v[68:71]
	v_mfma_f32_16x16x32_bf16 v[116:119], v[176:179], v[192:195], v[116:119]
	v_mfma_f32_16x16x32_bf16 v[108:111], v[184:187], v[192:195], v[108:111]
	v_mfma_f32_16x16x32_bf16 v[100:103], v[176:179], v[200:203], v[100:103]
	v_mfma_f32_16x16x32_bf16 v[92:95], v[184:187], v[200:203], v[92:95]
	v_mfma_f32_16x16x32_bf16 v[84:87], v[176:179], v[208:211], v[84:87]
	v_mfma_f32_16x16x32_bf16 v[76:79], v[184:187], v[208:211], v[76:79]
	v_mfma_f32_16x16x32_bf16 v[72:75], v[176:179], v[230:233], v[72:75]
	v_mfma_f32_16x16x32_bf16 v[68:71], v[184:187], v[230:233], v[68:71]
	s_barrier
; #define PG8_STAGE(bufoff, gbase, voff) do { _Pragma("unroll") for (int _i = 0; _i < 2; ++_i) \
;         __builtin_amdgcn_global_load_lds((const unsigned*)((const char*)(gbase) + (voff)[_i]), (PG8_LAS unsigned*)(lds + (bufoff) + ldsw + _i * 8192), 16, 0, 0); } while (0)
; #define PG8_LDA(dst, b, h) do { _Pragma("unroll") for (int m = 0; m < 4; ++m) _Pragma("unroll") for (int k = 0; k < 2; ++k) dst[m][k] = *(const PG8_LAS bf16x8*)(lds + PG8_SA(b, h) + aoffk[k] + m * 2048); } while (0)
; #define PG8_MMA(ai, bj, At, Bt) do { __builtin_amdgcn_s_setprio(1); _Pragma("unroll") for (int m = 0; m < 4; ++m) _Pragma("unroll") for (int n = 0; n < 2; ++n) _Pragma("unroll") for (int k = 0; k < 2; ++k) \
;         acc[ai][bj][m][n] = __builtin_amdgcn_mfma_f32_16x16x32_bf16(Bt[n][k], At[m][k], acc[ai][bj][m][n], 0, 0, 0); __builtin_amdgcn_s_setprio(0); } while (0)
; #define PG8_WAIT_V(n) asm volatile("s_waitcnt vmcnt(" #n ")" ::: "memory")
; #define PG8_WAIT_L(n) asm volatile("s_waitcnt lgkmcnt(" #n ")" ::: "memory")
; #define PG8_BAR __builtin_amdgcn_s_barrier()
; #define PG8_SCHED __builtin_amdgcn_sched_barrier(0)
; template <class Epi, class Sched, bool ALIGN_EPI = false, bool SP2 = false>
; __device__ __forceinline__ void gemm_phase(PG8_LAS unsigned char* lds, const Gemm g, const Sched& S, const Epi& E) {
;     ...
;             PG8_LDA(At, 1, 1); PG8_STAGE(PG8_SB(1, 0), b3, voffB); PG8_STAGE(PG8_SB(1, 1), b3 + hstepB, voffB); PG8_STAGE(PG8_SA(1, 0), a3, voffA);
;             PG8_WAIT_V(8); PG8_WAIT_L(0); PG8_BAR; PG8_MMA(1, 0, At, B0); PG8_MMA(1, 1, At, B1); PG8_BAR; PG8_SCHED;
	s_add_i32 s12, s51, s25
	v_lshl_add_u64 v[142:143], v[142:143], 0, s[58:59]
	s_mov_b32 m0, s12
	ds_read_b128 v[188:191], v148 offset:49152
	ds_read_b128 v[192:195], v148 offset:50176
	ds_read_b128 v[196:199], v148 offset:51200
	ds_read_b128 v[200:203], v148 offset:52224
	ds_read_b128 v[204:207], v148 offset:53248
	ds_read_b128 v[208:211], v148 offset:54272
	ds_read_b128 v[226:229], v148 offset:55296
	ds_read_b128 v[230:233], v148 offset:56320
	global_load_lds_dwordx4 v[142:143], off
	s_add_i32 m0, s12, 0x2000
	s_add_u32 s12, s16, 0x160080
	v_lshl_add_u64 v[142:143], v[166:167], 0, s[58:59]
	s_addc_u32 s13, s17, 0
	s_add_i32 s16, s52, s25
	global_load_lds_dwordx4 v[142:143], off
	v_lshl_add_u64 v[142:143], s[12:13], 0, v[2:3]
	s_mov_b32 m0, s16
	s_nop 0
	global_load_lds_dwordx4 v[142:143], off
	v_lshl_add_u64 v[142:143], s[12:13], 0, v[136:137]
	s_add_i32 m0, s16, 0x2000
	s_nop 0
	global_load_lds_dwordx4 v[142:143], off
	v_lshl_add_u64 v[142:143], v[212:213], 0, s[58:59]
	s_mov_b32 m0, s36
	s_nop 0
	global_load_lds_dwordx4 v[142:143], off
	v_lshl_add_u64 v[142:143], v[220:221], 0, s[58:59]
	s_mov_b32 m0, s37
	s_nop 0
	global_load_lds_dwordx4 v[142:143], off
	s_waitcnt vmcnt(8)
	s_waitcnt lgkmcnt(0)
	s_barrier
	v_mfma_f32_16x16x32_bf16 v[64:67], v[150:153], v[188:191], v[64:67]
	v_mfma_f32_16x16x32_bf16 v[60:63], v[158:161], v[188:191], v[60:63]
	v_mfma_f32_16x16x32_bf16 v[56:59], v[150:153], v[196:199], v[56:59]
	v_mfma_f32_16x16x32_bf16 v[48:51], v[158:161], v[196:199], v[48:51]
	v_mfma_f32_16x16x32_bf16 v[40:43], v[150:153], v[204:207], v[40:43]
	v_mfma_f32_16x16x32_bf16 v[32:35], v[158:161], v[204:207], v[32:35]
	v_mfma_f32_16x16x32_bf16 v[24:27], v[150:153], v[226:229], v[24:27]
	v_mfma_f32_16x16x32_bf16 v[16:19], v[158:161], v[226:229], v[16:19]
	v_mfma_f32_16x16x32_bf16 v[64:67], v[154:157], v[192:195], v[64:67]
	v_mfma_f32_16x16x32_bf16 v[60:63], v[162:165], v[192:195], v[60:63]
	v_mfma_f32_16x16x32_bf16 v[56:59], v[154:157], v[200:203], v[56:59]
	v_mfma_f32_16x16x32_bf16 v[48:51], v[162:165], v[200:203], v[48:51]
	v_mfma_f32_16x16x32_bf16 v[40:43], v[154:157], v[208:211], v[40:43]
	v_mfma_f32_16x16x32_bf16 v[32:35], v[162:165], v[208:211], v[32:35]
	v_mfma_f32_16x16x32_bf16 v[24:27], v[154:157], v[230:233], v[24:27]
	v_mfma_f32_16x16x32_bf16 v[16:19], v[162:165], v[230:233], v[16:19]
	v_mfma_f32_16x16x32_bf16 v[52:55], v[172:175], v[188:191], v[52:55]
	v_mfma_f32_16x16x32_bf16 v[44:47], v[180:183], v[188:191], v[44:47]
	v_mfma_f32_16x16x32_bf16 v[36:39], v[172:175], v[196:199], v[36:39]
	v_mfma_f32_16x16x32_bf16 v[28:31], v[180:183], v[196:199], v[28:31]
	v_mfma_f32_16x16x32_bf16 v[20:23], v[172:175], v[204:207], v[20:23]
	v_mfma_f32_16x16x32_bf16 v[12:15], v[180:183], v[204:207], v[12:15]
	v_mfma_f32_16x16x32_bf16 v[8:11], v[172:175], v[226:229], v[8:11]
	v_mfma_f32_16x16x32_bf16 v[4:7], v[180:183], v[226:229], v[4:7]
	v_mfma_f32_16x16x32_bf16 v[52:55], v[176:179], v[192:195], v[52:55]
	v_mfma_f32_16x16x32_bf16 v[44:47], v[184:187], v[192:195], v[44:47]
	v_mfma_f32_16x16x32_bf16 v[36:39], v[176:179], v[200:203], v[36:39]
	v_mfma_f32_16x16x32_bf16 v[28:31], v[184:187], v[200:203], v[28:31]
	v_mfma_f32_16x16x32_bf16 v[20:23], v[176:179], v[208:211], v[20:23]
	v_mfma_f32_16x16x32_bf16 v[12:15], v[184:187], v[208:211], v[12:15]
	v_mfma_f32_16x16x32_bf16 v[8:11], v[176:179], v[230:233], v[8:11]
	v_mfma_f32_16x16x32_bf16 v[4:7], v[184:187], v[230:233], v[4:7]
	s_barrier
	s_add_u32 s48, s48, 0x100
	s_addc_u32 s49, s49, 0
	s_cmp_ge_i32 s50, s43
	s_mov_b64 s[12:13], s[14:15]
	s_mov_b32 s16, s50
	s_cbranch_scc0 .LBB0_1592
	s_and_b64 vcc, exec, s[4:5]
	s_cbranch_vccz .LBB0_1595
	s_barrier
